# scan waves: forced lgkmcnt wait only on even steps (covers the previous step's first vector load), odd steps rely on it
# speedup vs baseline: 1.0026x; 1.0026x over previous
.Lsc_S_loop:
	s_waitcnt lgkmcnt(3)
	v_pk_fma_f32 v[10:11], v[80:81], v[30:31], v[16:17] op_sel_hi:[1,0,1] neg_lo:[0,1,0] neg_hi:[0,1,0]
	v_pk_fma_f32 v[8:9], v[82:83], v[30:31], v[18:19] op_sel_hi:[1,0,1] neg_lo:[0,1,0] neg_hi:[0,1,0]
	v_pk_mul_f32 v[24:25], v[10:11], v[84:85] op_sel:[0,0] op_sel_hi:[0,1]
	v_pk_fma_f32 v[24:25], v[10:11], v[86:87], v[24:25] op_sel:[1,0,0] op_sel_hi:[1,1,1]
	v_pk_fma_f32 v[24:25], v[8:9], v[88:89], v[24:25] op_sel:[0,0,0] op_sel_hi:[0,1,1]
	v_pk_fma_f32 v[24:25], v[8:9], v[90:91], v[24:25] op_sel:[1,0,0] op_sel_hi:[1,1,1]
	v_pk_fma_f32 v[16:17], v[92:93], v[156:157], v[10:11] op_sel:[0,1,0] op_sel_hi:[1,1,1]
	v_pk_fma_f32 v[18:19], v[94:95], v[156:157], v[8:9] op_sel:[0,1,0] op_sel_hi:[1,1,1]
	v_add_f32_dpp v15, v24, v24 row_ror:8 row_mask:0xf bank_mask:0xf bound_ctrl:1
	v_add_f32_dpp v32, v25, v25 row_ror:8 row_mask:0xf bank_mask:0xf bound_ctrl:1
	ds_read_b128 v[124:127], v34 offset:3072
	v_add_f32_dpp v15, v15, v15 row_ror:4 row_mask:0xf bank_mask:0xf bound_ctrl:1
	ds_read_b128 v[128:131], v34 offset:3328
	ds_read_b128 v[132:135], v34 offset:3584
	v_add_f32_dpp v15, v15, v15 row_ror:2 row_mask:0xf bank_mask:0xf bound_ctrl:1
	ds_read_b128 v[136:139], v34 offset:3840
	ds_read_b128 v[160:163], v35 offset:16
	v_add_f32_dpp v30, v15, v15 row_ror:1 row_mask:0xf bank_mask:0xf bound_ctrl:1
	v_pk_fma_f32 v[10:11], v[96:97], v[30:31], v[16:17] op_sel_hi:[1,0,1] neg_lo:[0,1,0] neg_hi:[0,1,0]
	v_pk_fma_f32 v[8:9], v[98:99], v[30:31], v[18:19] op_sel_hi:[1,0,1] neg_lo:[0,1,0] neg_hi:[0,1,0]
	v_pk_mul_f32 v[24:25], v[10:11], v[100:101] op_sel:[0,0] op_sel_hi:[0,1]
	v_pk_fma_f32 v[24:25], v[10:11], v[102:103], v[24:25] op_sel:[1,0,0] op_sel_hi:[1,1,1]
	v_pk_fma_f32 v[24:25], v[8:9], v[104:105], v[24:25] op_sel:[0,0,0] op_sel_hi:[0,1,1]
	v_pk_fma_f32 v[24:25], v[8:9], v[106:107], v[24:25] op_sel:[1,0,0] op_sel_hi:[1,1,1]
	v_pk_fma_f32 v[16:17], v[108:109], v[158:159], v[10:11] op_sel_hi:[1,0,1]
	v_pk_fma_f32 v[18:19], v[110:111], v[158:159], v[8:9] op_sel_hi:[1,0,1]
	v_add_f32_dpp v15, v24, v24 row_ror:8 row_mask:0xf bank_mask:0xf bound_ctrl:1
	v_add_f32_dpp v33, v25, v25 row_ror:8 row_mask:0xf bank_mask:0xf bound_ctrl:1
	ds_read_b128 v[76:79], v34 offset:4096
	v_add_f32_dpp v15, v15, v15 row_ror:4 row_mask:0xf bank_mask:0xf bound_ctrl:1
	ds_read_b128 v[80:83], v34 offset:4352
	ds_read_b128 v[84:87], v34 offset:4608
	v_add_f32_dpp v15, v15, v15 row_ror:2 row_mask:0xf bank_mask:0xf bound_ctrl:1
	ds_read_b128 v[88:91], v34 offset:4864
	s_nop 0
	v_add_f32_dpp v30, v15, v15 row_ror:1 row_mask:0xf bank_mask:0xf bound_ctrl:1
	ds_write2st64_b32 v37, v32, v33 offset0:0 offset1:2
	s_waitcnt lgkmcnt(4)
	v_pk_fma_f32 v[10:11], v[112:113], v[30:31], v[16:17] op_sel_hi:[1,0,1] neg_lo:[0,1,0] neg_hi:[0,1,0]
	v_pk_fma_f32 v[8:9], v[114:115], v[30:31], v[18:19] op_sel_hi:[1,0,1] neg_lo:[0,1,0] neg_hi:[0,1,0]
	v_pk_mul_f32 v[24:25], v[10:11], v[116:117] op_sel:[0,0] op_sel_hi:[0,1]
	v_pk_fma_f32 v[24:25], v[10:11], v[118:119], v[24:25] op_sel:[1,0,0] op_sel_hi:[1,1,1]
	v_pk_fma_f32 v[24:25], v[8:9], v[120:121], v[24:25] op_sel:[0,0,0] op_sel_hi:[0,1,1]
	v_pk_fma_f32 v[24:25], v[8:9], v[122:123], v[24:25] op_sel:[1,0,0] op_sel_hi:[1,1,1]
	v_pk_fma_f32 v[16:17], v[124:125], v[158:159], v[10:11] op_sel:[0,1,0] op_sel_hi:[1,1,1]
	v_pk_fma_f32 v[18:19], v[126:127], v[158:159], v[8:9] op_sel:[0,1,0] op_sel_hi:[1,1,1]
	v_add_f32_dpp v15, v24, v24 row_ror:8 row_mask:0xf bank_mask:0xf bound_ctrl:1
	v_add_f32_dpp v32, v25, v25 row_ror:8 row_mask:0xf bank_mask:0xf bound_ctrl:1
	ds_read_b128 v[92:95], v34 offset:5120
	v_add_f32_dpp v15, v15, v15 row_ror:4 row_mask:0xf bank_mask:0xf bound_ctrl:1
	ds_read_b128 v[96:99], v34 offset:5376
	ds_read_b128 v[100:103], v34 offset:5632
	v_add_f32_dpp v15, v15, v15 row_ror:2 row_mask:0xf bank_mask:0xf bound_ctrl:1
	ds_read_b128 v[104:107], v34 offset:5888
	s_nop 0
	v_add_f32_dpp v30, v15, v15 row_ror:1 row_mask:0xf bank_mask:0xf bound_ctrl:1
	v_pk_fma_f32 v[10:11], v[128:129], v[30:31], v[16:17] op_sel_hi:[1,0,1] neg_lo:[0,1,0] neg_hi:[0,1,0]
	v_pk_fma_f32 v[8:9], v[130:131], v[30:31], v[18:19] op_sel_hi:[1,0,1] neg_lo:[0,1,0] neg_hi:[0,1,0]
	v_pk_mul_f32 v[24:25], v[10:11], v[132:133] op_sel:[0,0] op_sel_hi:[0,1]
	v_pk_fma_f32 v[24:25], v[10:11], v[134:135], v[24:25] op_sel:[1,0,0] op_sel_hi:[1,1,1]
	v_pk_fma_f32 v[24:25], v[8:9], v[136:137], v[24:25] op_sel:[0,0,0] op_sel_hi:[0,1,1]
	v_pk_fma_f32 v[24:25], v[8:9], v[138:139], v[24:25] op_sel:[1,0,0] op_sel_hi:[1,1,1]
	v_pk_fma_f32 v[16:17], v[76:77], v[160:161], v[10:11] op_sel_hi:[1,0,1]
	v_pk_fma_f32 v[18:19], v[78:79], v[160:161], v[8:9] op_sel_hi:[1,0,1]
	v_add_f32_dpp v15, v24, v24 row_ror:8 row_mask:0xf bank_mask:0xf bound_ctrl:1
	v_add_f32_dpp v33, v25, v25 row_ror:8 row_mask:0xf bank_mask:0xf bound_ctrl:1
	ds_read_b128 v[108:111], v34 offset:6144
	v_add_f32_dpp v15, v15, v15 row_ror:4 row_mask:0xf bank_mask:0xf bound_ctrl:1
	ds_read_b128 v[112:115], v34 offset:6400
	ds_read_b128 v[116:119], v34 offset:6656
	v_add_f32_dpp v15, v15, v15 row_ror:2 row_mask:0xf bank_mask:0xf bound_ctrl:1
	ds_read_b128 v[120:123], v34 offset:6912
	ds_read_b128 v[140:143], v34 offset:33792
	v_add_f32_dpp v30, v15, v15 row_ror:1 row_mask:0xf bank_mask:0xf bound_ctrl:1
	ds_write2st64_b32 v37, v32, v33 offset0:4 offset1:6
	s_waitcnt lgkmcnt(5)
	v_pk_fma_f32 v[10:11], v[80:81], v[30:31], v[16:17] op_sel_hi:[1,0,1] neg_lo:[0,1,0] neg_hi:[0,1,0]
	v_pk_fma_f32 v[8:9], v[82:83], v[30:31], v[18:19] op_sel_hi:[1,0,1] neg_lo:[0,1,0] neg_hi:[0,1,0]
	v_pk_mul_f32 v[24:25], v[10:11], v[84:85] op_sel:[0,0] op_sel_hi:[0,1]
	v_pk_fma_f32 v[24:25], v[10:11], v[86:87], v[24:25] op_sel:[1,0,0] op_sel_hi:[1,1,1]
	v_pk_fma_f32 v[24:25], v[8:9], v[88:89], v[24:25] op_sel:[0,0,0] op_sel_hi:[0,1,1]
	v_pk_fma_f32 v[24:25], v[8:9], v[90:91], v[24:25] op_sel:[1,0,0] op_sel_hi:[1,1,1]
	v_pk_fma_f32 v[16:17], v[92:93], v[160:161], v[10:11] op_sel:[0,1,0] op_sel_hi:[1,1,1]
	v_pk_fma_f32 v[18:19], v[94:95], v[160:161], v[8:9] op_sel:[0,1,0] op_sel_hi:[1,1,1]
	v_add_f32_dpp v15, v24, v24 row_ror:8 row_mask:0xf bank_mask:0xf bound_ctrl:1
	v_add_f32_dpp v32, v25, v25 row_ror:8 row_mask:0xf bank_mask:0xf bound_ctrl:1
	ds_read_b128 v[124:127], v34 offset:7168
	v_add_f32_dpp v15, v15, v15 row_ror:4 row_mask:0xf bank_mask:0xf bound_ctrl:1
	ds_read_b128 v[128:131], v34 offset:7424
	ds_read_b128 v[132:135], v34 offset:7680
	v_add_f32_dpp v15, v15, v15 row_ror:2 row_mask:0xf bank_mask:0xf bound_ctrl:1
	ds_read_b128 v[136:139], v34 offset:7936
	ds_read_b128 v[156:159], v35 offset:32
	v_add_f32_dpp v30, v15, v15 row_ror:1 row_mask:0xf bank_mask:0xf bound_ctrl:1
	v_pk_fma_f32 v[10:11], v[96:97], v[30:31], v[16:17] op_sel_hi:[1,0,1] neg_lo:[0,1,0] neg_hi:[0,1,0]
	v_pk_fma_f32 v[8:9], v[98:99], v[30:31], v[18:19] op_sel_hi:[1,0,1] neg_lo:[0,1,0] neg_hi:[0,1,0]
	v_pk_mul_f32 v[24:25], v[10:11], v[100:101] op_sel:[0,0] op_sel_hi:[0,1]
	v_pk_fma_f32 v[24:25], v[10:11], v[102:103], v[24:25] op_sel:[1,0,0] op_sel_hi:[1,1,1]
	v_pk_fma_f32 v[24:25], v[8:9], v[104:105], v[24:25] op_sel:[0,0,0] op_sel_hi:[0,1,1]
	v_pk_fma_f32 v[24:25], v[8:9], v[106:107], v[24:25] op_sel:[1,0,0] op_sel_hi:[1,1,1]
	v_pk_fma_f32 v[16:17], v[108:109], v[162:163], v[10:11] op_sel_hi:[1,0,1]
	v_pk_fma_f32 v[18:19], v[110:111], v[162:163], v[8:9] op_sel_hi:[1,0,1]
	v_add_f32_dpp v15, v24, v24 row_ror:8 row_mask:0xf bank_mask:0xf bound_ctrl:1
	v_add_f32_dpp v33, v25, v25 row_ror:8 row_mask:0xf bank_mask:0xf bound_ctrl:1
	ds_read_b128 v[76:79], v34 offset:8192
	v_add_f32_dpp v15, v15, v15 row_ror:4 row_mask:0xf bank_mask:0xf bound_ctrl:1
	ds_read_b128 v[80:83], v34 offset:8448
	ds_read_b128 v[84:87], v34 offset:8704
	v_add_f32_dpp v15, v15, v15 row_ror:2 row_mask:0xf bank_mask:0xf bound_ctrl:1
	ds_read_b128 v[88:91], v34 offset:8960
	ds_read_b128 v[144:147], v34 offset:33024
	v_add_f32_dpp v30, v15, v15 row_ror:1 row_mask:0xf bank_mask:0xf bound_ctrl:1
	ds_write2st64_b32 v37, v32, v33 offset0:8 offset1:10
	s_waitcnt lgkmcnt(5)
	v_pk_fma_f32 v[10:11], v[112:113], v[30:31], v[16:17] op_sel_hi:[1,0,1] neg_lo:[0,1,0] neg_hi:[0,1,0]
	v_pk_fma_f32 v[8:9], v[114:115], v[30:31], v[18:19] op_sel_hi:[1,0,1] neg_lo:[0,1,0] neg_hi:[0,1,0]
	v_pk_mul_f32 v[24:25], v[10:11], v[116:117] op_sel:[0,0] op_sel_hi:[0,1]
	v_pk_fma_f32 v[24:25], v[10:11], v[118:119], v[24:25] op_sel:[1,0,0] op_sel_hi:[1,1,1]
	v_pk_fma_f32 v[24:25], v[8:9], v[120:121], v[24:25] op_sel:[0,0,0] op_sel_hi:[0,1,1]
	v_pk_fma_f32 v[24:25], v[8:9], v[122:123], v[24:25] op_sel:[1,0,0] op_sel_hi:[1,1,1]
	v_pk_fma_f32 v[16:17], v[124:125], v[162:163], v[10:11] op_sel:[0,1,0] op_sel_hi:[1,1,1]
	v_pk_fma_f32 v[18:19], v[126:127], v[162:163], v[8:9] op_sel:[0,1,0] op_sel_hi:[1,1,1]
	v_add_f32_dpp v15, v24, v24 row_ror:8 row_mask:0xf bank_mask:0xf bound_ctrl:1
	v_add_f32_dpp v32, v25, v25 row_ror:8 row_mask:0xf bank_mask:0xf bound_ctrl:1
	ds_read_b128 v[92:95], v34 offset:9216
	v_add_f32_dpp v15, v15, v15 row_ror:4 row_mask:0xf bank_mask:0xf bound_ctrl:1
	ds_read_b128 v[96:99], v34 offset:9472
	ds_read_b128 v[100:103], v34 offset:9728
	v_add_f32_dpp v15, v15, v15 row_ror:2 row_mask:0xf bank_mask:0xf bound_ctrl:1
	ds_read_b128 v[104:107], v34 offset:9984
	s_nop 0
	v_add_f32_dpp v30, v15, v15 row_ror:1 row_mask:0xf bank_mask:0xf bound_ctrl:1
	v_pk_fma_f32 v[10:11], v[128:129], v[30:31], v[16:17] op_sel_hi:[1,0,1] neg_lo:[0,1,0] neg_hi:[0,1,0]
	v_pk_fma_f32 v[8:9], v[130:131], v[30:31], v[18:19] op_sel_hi:[1,0,1] neg_lo:[0,1,0] neg_hi:[0,1,0]
	v_pk_mul_f32 v[24:25], v[10:11], v[132:133] op_sel:[0,0] op_sel_hi:[0,1]
	v_pk_fma_f32 v[24:25], v[10:11], v[134:135], v[24:25] op_sel:[1,0,0] op_sel_hi:[1,1,1]
	v_pk_fma_f32 v[24:25], v[8:9], v[136:137], v[24:25] op_sel:[0,0,0] op_sel_hi:[0,1,1]
	v_pk_fma_f32 v[24:25], v[8:9], v[138:139], v[24:25] op_sel:[1,0,0] op_sel_hi:[1,1,1]
	s_nop 1
	v_add_f32_dpp v33, v25, v25 row_ror:8 row_mask:0xf bank_mask:0xf bound_ctrl:1
	ds_write2st64_b32 v37, v32, v33 offset0:12 offset1:14
	v_pk_mul_f32 v[10:11], v[10:11], v[140:141]
	v_pk_mul_f32 v[8:9], v[8:9], v[142:143]
	s_waitcnt lgkmcnt(6)
	v_pk_mul_f32 v[24:25], v[10:11], v[144:145]
	v_pk_fma_f32 v[24:25], v[8:9], v[146:147], v[24:25]
	v_add_f32_e32 v24, v24, v25
	v_pk_fma_f32 v[16:17], v[76:77], v[156:157], v[10:11] op_sel_hi:[1,0,1]
	v_pk_fma_f32 v[18:19], v[78:79], v[156:157], v[8:9] op_sel_hi:[1,0,1]
	v_add_f32_dpp v15, v24, v24 row_ror:8 row_mask:0xf bank_mask:0xf bound_ctrl:1
	ds_read_b128 v[108:111], v34 offset:10240
	ds_read_b128 v[112:115], v34 offset:10496
	v_add_f32_dpp v15, v15, v15 row_ror:4 row_mask:0xf bank_mask:0xf bound_ctrl:1
	ds_read_b128 v[116:119], v34 offset:10752
	ds_read_b128 v[120:123], v34 offset:11008
	v_add_f32_dpp v15, v15, v15 row_ror:2 row_mask:0xf bank_mask:0xf bound_ctrl:1
	s_nop 1
	v_add_f32_dpp v30, v15, v15 row_ror:1 row_mask:0xf bank_mask:0xf bound_ctrl:1
	s_waitcnt lgkmcnt(3)
	v_pk_fma_f32 v[10:11], v[80:81], v[30:31], v[16:17] op_sel_hi:[1,0,1] neg_lo:[0,1,0] neg_hi:[0,1,0]
	v_pk_fma_f32 v[8:9], v[82:83], v[30:31], v[18:19] op_sel_hi:[1,0,1] neg_lo:[0,1,0] neg_hi:[0,1,0]
	v_pk_mul_f32 v[24:25], v[10:11], v[84:85] op_sel:[0,0] op_sel_hi:[0,1]
	v_pk_fma_f32 v[24:25], v[10:11], v[86:87], v[24:25] op_sel:[1,0,0] op_sel_hi:[1,1,1]
	v_pk_fma_f32 v[24:25], v[8:9], v[88:89], v[24:25] op_sel:[0,0,0] op_sel_hi:[0,1,1]
	v_pk_fma_f32 v[24:25], v[8:9], v[90:91], v[24:25] op_sel:[1,0,0] op_sel_hi:[1,1,1]
	v_pk_fma_f32 v[16:17], v[92:93], v[156:157], v[10:11] op_sel:[0,1,0] op_sel_hi:[1,1,1]
	v_pk_fma_f32 v[18:19], v[94:95], v[156:157], v[8:9] op_sel:[0,1,0] op_sel_hi:[1,1,1]
	v_add_f32_dpp v15, v24, v24 row_ror:8 row_mask:0xf bank_mask:0xf bound_ctrl:1
	v_add_f32_dpp v32, v25, v25 row_ror:8 row_mask:0xf bank_mask:0xf bound_ctrl:1
	ds_read_b128 v[124:127], v34 offset:11264
	v_add_f32_dpp v15, v15, v15 row_ror:4 row_mask:0xf bank_mask:0xf bound_ctrl:1
	ds_read_b128 v[128:131], v34 offset:11520
	ds_read_b128 v[132:135], v34 offset:11776
	v_add_f32_dpp v15, v15, v15 row_ror:2 row_mask:0xf bank_mask:0xf bound_ctrl:1
	ds_read_b128 v[136:139], v34 offset:12032
	ds_read_b128 v[160:163], v35 offset:48
	v_add_f32_dpp v30, v15, v15 row_ror:1 row_mask:0xf bank_mask:0xf bound_ctrl:1
	v_pk_fma_f32 v[10:11], v[96:97], v[30:31], v[16:17] op_sel_hi:[1,0,1] neg_lo:[0,1,0] neg_hi:[0,1,0]
	v_pk_fma_f32 v[8:9], v[98:99], v[30:31], v[18:19] op_sel_hi:[1,0,1] neg_lo:[0,1,0] neg_hi:[0,1,0]
	v_pk_mul_f32 v[24:25], v[10:11], v[100:101] op_sel:[0,0] op_sel_hi:[0,1]
	v_pk_fma_f32 v[24:25], v[10:11], v[102:103], v[24:25] op_sel:[1,0,0] op_sel_hi:[1,1,1]
	v_pk_fma_f32 v[24:25], v[8:9], v[104:105], v[24:25] op_sel:[0,0,0] op_sel_hi:[0,1,1]
	v_pk_fma_f32 v[24:25], v[8:9], v[106:107], v[24:25] op_sel:[1,0,0] op_sel_hi:[1,1,1]
	v_pk_fma_f32 v[16:17], v[108:109], v[158:159], v[10:11] op_sel_hi:[1,0,1]
	v_pk_fma_f32 v[18:19], v[110:111], v[158:159], v[8:9] op_sel_hi:[1,0,1]
	v_add_f32_dpp v15, v24, v24 row_ror:8 row_mask:0xf bank_mask:0xf bound_ctrl:1
	v_add_f32_dpp v33, v25, v25 row_ror:8 row_mask:0xf bank_mask:0xf bound_ctrl:1
	ds_read_b128 v[76:79], v34 offset:12288
	v_add_f32_dpp v15, v15, v15 row_ror:4 row_mask:0xf bank_mask:0xf bound_ctrl:1
	ds_read_b128 v[80:83], v34 offset:12544
	ds_read_b128 v[84:87], v34 offset:12800
	v_add_f32_dpp v15, v15, v15 row_ror:2 row_mask:0xf bank_mask:0xf bound_ctrl:1
	ds_read_b128 v[88:91], v34 offset:13056
	s_nop 0
	v_add_f32_dpp v30, v15, v15 row_ror:1 row_mask:0xf bank_mask:0xf bound_ctrl:1
	ds_write2st64_b32 v37, v32, v33 offset0:16 offset1:18
	s_waitcnt lgkmcnt(4)
	v_pk_fma_f32 v[10:11], v[112:113], v[30:31], v[16:17] op_sel_hi:[1,0,1] neg_lo:[0,1,0] neg_hi:[0,1,0]
	v_pk_fma_f32 v[8:9], v[114:115], v[30:31], v[18:19] op_sel_hi:[1,0,1] neg_lo:[0,1,0] neg_hi:[0,1,0]
	v_pk_mul_f32 v[24:25], v[10:11], v[116:117] op_sel:[0,0] op_sel_hi:[0,1]
	v_pk_fma_f32 v[24:25], v[10:11], v[118:119], v[24:25] op_sel:[1,0,0] op_sel_hi:[1,1,1]
	v_pk_fma_f32 v[24:25], v[8:9], v[120:121], v[24:25] op_sel:[0,0,0] op_sel_hi:[0,1,1]
	v_pk_fma_f32 v[24:25], v[8:9], v[122:123], v[24:25] op_sel:[1,0,0] op_sel_hi:[1,1,1]
	v_pk_fma_f32 v[16:17], v[124:125], v[158:159], v[10:11] op_sel:[0,1,0] op_sel_hi:[1,1,1]
	v_pk_fma_f32 v[18:19], v[126:127], v[158:159], v[8:9] op_sel:[0,1,0] op_sel_hi:[1,1,1]
	v_add_f32_dpp v15, v24, v24 row_ror:8 row_mask:0xf bank_mask:0xf bound_ctrl:1
	v_add_f32_dpp v32, v25, v25 row_ror:8 row_mask:0xf bank_mask:0xf bound_ctrl:1
	ds_read_b128 v[92:95], v34 offset:13312
	v_add_f32_dpp v15, v15, v15 row_ror:4 row_mask:0xf bank_mask:0xf bound_ctrl:1
	ds_read_b128 v[96:99], v34 offset:13568
	ds_read_b128 v[100:103], v34 offset:13824
	v_add_f32_dpp v15, v15, v15 row_ror:2 row_mask:0xf bank_mask:0xf bound_ctrl:1
	ds_read_b128 v[104:107], v34 offset:14080
	s_nop 0
	v_add_f32_dpp v30, v15, v15 row_ror:1 row_mask:0xf bank_mask:0xf bound_ctrl:1
	v_pk_fma_f32 v[10:11], v[128:129], v[30:31], v[16:17] op_sel_hi:[1,0,1] neg_lo:[0,1,0] neg_hi:[0,1,0]
	v_pk_fma_f32 v[8:9], v[130:131], v[30:31], v[18:19] op_sel_hi:[1,0,1] neg_lo:[0,1,0] neg_hi:[0,1,0]
	v_pk_mul_f32 v[24:25], v[10:11], v[132:133] op_sel:[0,0] op_sel_hi:[0,1]
	v_pk_fma_f32 v[24:25], v[10:11], v[134:135], v[24:25] op_sel:[1,0,0] op_sel_hi:[1,1,1]
	v_pk_fma_f32 v[24:25], v[8:9], v[136:137], v[24:25] op_sel:[0,0,0] op_sel_hi:[0,1,1]
	v_pk_fma_f32 v[24:25], v[8:9], v[138:139], v[24:25] op_sel:[1,0,0] op_sel_hi:[1,1,1]
	v_pk_fma_f32 v[16:17], v[76:77], v[160:161], v[10:11] op_sel_hi:[1,0,1]
	v_pk_fma_f32 v[18:19], v[78:79], v[160:161], v[8:9] op_sel_hi:[1,0,1]
	v_add_f32_dpp v15, v24, v24 row_ror:8 row_mask:0xf bank_mask:0xf bound_ctrl:1
	v_add_f32_dpp v33, v25, v25 row_ror:8 row_mask:0xf bank_mask:0xf bound_ctrl:1
	ds_read_b128 v[108:111], v34 offset:14336
	v_add_f32_dpp v15, v15, v15 row_ror:4 row_mask:0xf bank_mask:0xf bound_ctrl:1
	ds_read_b128 v[112:115], v34 offset:14592
	ds_read_b128 v[116:119], v34 offset:14848
	v_add_f32_dpp v15, v15, v15 row_ror:2 row_mask:0xf bank_mask:0xf bound_ctrl:1
	ds_read_b128 v[120:123], v34 offset:15104
	ds_read_b128 v[140:143], v34 offset:34048
	v_add_f32_dpp v30, v15, v15 row_ror:1 row_mask:0xf bank_mask:0xf bound_ctrl:1
	ds_write2st64_b32 v37, v32, v33 offset0:20 offset1:22
	s_waitcnt lgkmcnt(5)
	v_pk_fma_f32 v[10:11], v[80:81], v[30:31], v[16:17] op_sel_hi:[1,0,1] neg_lo:[0,1,0] neg_hi:[0,1,0]
	v_pk_fma_f32 v[8:9], v[82:83], v[30:31], v[18:19] op_sel_hi:[1,0,1] neg_lo:[0,1,0] neg_hi:[0,1,0]
	v_pk_mul_f32 v[24:25], v[10:11], v[84:85] op_sel:[0,0] op_sel_hi:[0,1]
	v_pk_fma_f32 v[24:25], v[10:11], v[86:87], v[24:25] op_sel:[1,0,0] op_sel_hi:[1,1,1]
	v_pk_fma_f32 v[24:25], v[8:9], v[88:89], v[24:25] op_sel:[0,0,0] op_sel_hi:[0,1,1]
	v_pk_fma_f32 v[24:25], v[8:9], v[90:91], v[24:25] op_sel:[1,0,0] op_sel_hi:[1,1,1]
	v_pk_fma_f32 v[16:17], v[92:93], v[160:161], v[10:11] op_sel:[0,1,0] op_sel_hi:[1,1,1]
	v_pk_fma_f32 v[18:19], v[94:95], v[160:161], v[8:9] op_sel:[0,1,0] op_sel_hi:[1,1,1]
	v_add_f32_dpp v15, v24, v24 row_ror:8 row_mask:0xf bank_mask:0xf bound_ctrl:1
	v_add_f32_dpp v32, v25, v25 row_ror:8 row_mask:0xf bank_mask:0xf bound_ctrl:1
	ds_read_b128 v[124:127], v34 offset:15360
	v_add_f32_dpp v15, v15, v15 row_ror:4 row_mask:0xf bank_mask:0xf bound_ctrl:1
	ds_read_b128 v[128:131], v34 offset:15616
	ds_read_b128 v[132:135], v34 offset:15872
	v_add_f32_dpp v15, v15, v15 row_ror:2 row_mask:0xf bank_mask:0xf bound_ctrl:1
	ds_read_b128 v[136:139], v34 offset:16128
	ds_read_b128 v[156:159], v35 offset:64
	v_add_f32_dpp v30, v15, v15 row_ror:1 row_mask:0xf bank_mask:0xf bound_ctrl:1
	v_pk_fma_f32 v[10:11], v[96:97], v[30:31], v[16:17] op_sel_hi:[1,0,1] neg_lo:[0,1,0] neg_hi:[0,1,0]
	v_pk_fma_f32 v[8:9], v[98:99], v[30:31], v[18:19] op_sel_hi:[1,0,1] neg_lo:[0,1,0] neg_hi:[0,1,0]
	v_pk_mul_f32 v[24:25], v[10:11], v[100:101] op_sel:[0,0] op_sel_hi:[0,1]
	v_pk_fma_f32 v[24:25], v[10:11], v[102:103], v[24:25] op_sel:[1,0,0] op_sel_hi:[1,1,1]
	v_pk_fma_f32 v[24:25], v[8:9], v[104:105], v[24:25] op_sel:[0,0,0] op_sel_hi:[0,1,1]
	v_pk_fma_f32 v[24:25], v[8:9], v[106:107], v[24:25] op_sel:[1,0,0] op_sel_hi:[1,1,1]
	v_pk_fma_f32 v[16:17], v[108:109], v[162:163], v[10:11] op_sel_hi:[1,0,1]
	v_pk_fma_f32 v[18:19], v[110:111], v[162:163], v[8:9] op_sel_hi:[1,0,1]
	v_add_f32_dpp v15, v24, v24 row_ror:8 row_mask:0xf bank_mask:0xf bound_ctrl:1
	v_add_f32_dpp v33, v25, v25 row_ror:8 row_mask:0xf bank_mask:0xf bound_ctrl:1
	ds_read_b128 v[76:79], v34 offset:16384
	v_add_f32_dpp v15, v15, v15 row_ror:4 row_mask:0xf bank_mask:0xf bound_ctrl:1
	ds_read_b128 v[80:83], v34 offset:16640
	ds_read_b128 v[84:87], v34 offset:16896
	v_add_f32_dpp v15, v15, v15 row_ror:2 row_mask:0xf bank_mask:0xf bound_ctrl:1
	ds_read_b128 v[88:91], v34 offset:17152
	ds_read_b128 v[144:147], v34 offset:33280
	v_add_f32_dpp v30, v15, v15 row_ror:1 row_mask:0xf bank_mask:0xf bound_ctrl:1
	ds_write2st64_b32 v37, v32, v33 offset0:24 offset1:26
	s_waitcnt lgkmcnt(5)
	v_pk_fma_f32 v[10:11], v[112:113], v[30:31], v[16:17] op_sel_hi:[1,0,1] neg_lo:[0,1,0] neg_hi:[0,1,0]
	v_pk_fma_f32 v[8:9], v[114:115], v[30:31], v[18:19] op_sel_hi:[1,0,1] neg_lo:[0,1,0] neg_hi:[0,1,0]
	v_pk_mul_f32 v[24:25], v[10:11], v[116:117] op_sel:[0,0] op_sel_hi:[0,1]
	v_pk_fma_f32 v[24:25], v[10:11], v[118:119], v[24:25] op_sel:[1,0,0] op_sel_hi:[1,1,1]
	v_pk_fma_f32 v[24:25], v[8:9], v[120:121], v[24:25] op_sel:[0,0,0] op_sel_hi:[0,1,1]
	v_pk_fma_f32 v[24:25], v[8:9], v[122:123], v[24:25] op_sel:[1,0,0] op_sel_hi:[1,1,1]
	v_pk_fma_f32 v[16:17], v[124:125], v[162:163], v[10:11] op_sel:[0,1,0] op_sel_hi:[1,1,1]
	v_pk_fma_f32 v[18:19], v[126:127], v[162:163], v[8:9] op_sel:[0,1,0] op_sel_hi:[1,1,1]
	v_add_f32_dpp v15, v24, v24 row_ror:8 row_mask:0xf bank_mask:0xf bound_ctrl:1
	v_add_f32_dpp v32, v25, v25 row_ror:8 row_mask:0xf bank_mask:0xf bound_ctrl:1
	ds_read_b128 v[92:95], v34 offset:17408
	v_add_f32_dpp v15, v15, v15 row_ror:4 row_mask:0xf bank_mask:0xf bound_ctrl:1
	ds_read_b128 v[96:99], v34 offset:17664
	ds_read_b128 v[100:103], v34 offset:17920
	v_add_f32_dpp v15, v15, v15 row_ror:2 row_mask:0xf bank_mask:0xf bound_ctrl:1
	ds_read_b128 v[104:107], v34 offset:18176
	s_nop 0
	v_add_f32_dpp v30, v15, v15 row_ror:1 row_mask:0xf bank_mask:0xf bound_ctrl:1
	v_pk_fma_f32 v[10:11], v[128:129], v[30:31], v[16:17] op_sel_hi:[1,0,1] neg_lo:[0,1,0] neg_hi:[0,1,0]
	v_pk_fma_f32 v[8:9], v[130:131], v[30:31], v[18:19] op_sel_hi:[1,0,1] neg_lo:[0,1,0] neg_hi:[0,1,0]
	v_pk_mul_f32 v[24:25], v[10:11], v[132:133] op_sel:[0,0] op_sel_hi:[0,1]
	v_pk_fma_f32 v[24:25], v[10:11], v[134:135], v[24:25] op_sel:[1,0,0] op_sel_hi:[1,1,1]
	v_pk_fma_f32 v[24:25], v[8:9], v[136:137], v[24:25] op_sel:[0,0,0] op_sel_hi:[0,1,1]
	v_pk_fma_f32 v[24:25], v[8:9], v[138:139], v[24:25] op_sel:[1,0,0] op_sel_hi:[1,1,1]
	s_nop 1
	v_add_f32_dpp v33, v25, v25 row_ror:8 row_mask:0xf bank_mask:0xf bound_ctrl:1
	ds_write2st64_b32 v37, v32, v33 offset0:28 offset1:30
	v_pk_mul_f32 v[10:11], v[10:11], v[140:141]
	v_pk_mul_f32 v[8:9], v[8:9], v[142:143]
	s_waitcnt lgkmcnt(6)
	v_pk_mul_f32 v[24:25], v[10:11], v[144:145]
	v_pk_fma_f32 v[24:25], v[8:9], v[146:147], v[24:25]
	v_add_f32_e32 v24, v24, v25
	v_pk_fma_f32 v[16:17], v[76:77], v[156:157], v[10:11] op_sel_hi:[1,0,1]
	v_pk_fma_f32 v[18:19], v[78:79], v[156:157], v[8:9] op_sel_hi:[1,0,1]
	v_add_f32_dpp v15, v24, v24 row_ror:8 row_mask:0xf bank_mask:0xf bound_ctrl:1
	ds_read_b128 v[108:111], v34 offset:18432
	ds_read_b128 v[112:115], v34 offset:18688
	v_add_f32_dpp v15, v15, v15 row_ror:4 row_mask:0xf bank_mask:0xf bound_ctrl:1
	ds_read_b128 v[116:119], v34 offset:18944
	ds_read_b128 v[120:123], v34 offset:19200
	v_add_f32_dpp v15, v15, v15 row_ror:2 row_mask:0xf bank_mask:0xf bound_ctrl:1
	s_nop 1
	v_add_f32_dpp v30, v15, v15 row_ror:1 row_mask:0xf bank_mask:0xf bound_ctrl:1
	s_waitcnt lgkmcnt(3)
	v_pk_fma_f32 v[10:11], v[80:81], v[30:31], v[16:17] op_sel_hi:[1,0,1] neg_lo:[0,1,0] neg_hi:[0,1,0]
	v_pk_fma_f32 v[8:9], v[82:83], v[30:31], v[18:19] op_sel_hi:[1,0,1] neg_lo:[0,1,0] neg_hi:[0,1,0]
	v_pk_mul_f32 v[24:25], v[10:11], v[84:85] op_sel:[0,0] op_sel_hi:[0,1]
	v_pk_fma_f32 v[24:25], v[10:11], v[86:87], v[24:25] op_sel:[1,0,0] op_sel_hi:[1,1,1]
	v_pk_fma_f32 v[24:25], v[8:9], v[88:89], v[24:25] op_sel:[0,0,0] op_sel_hi:[0,1,1]
	v_pk_fma_f32 v[24:25], v[8:9], v[90:91], v[24:25] op_sel:[1,0,0] op_sel_hi:[1,1,1]
	v_pk_fma_f32 v[16:17], v[92:93], v[156:157], v[10:11] op_sel:[0,1,0] op_sel_hi:[1,1,1]
	v_pk_fma_f32 v[18:19], v[94:95], v[156:157], v[8:9] op_sel:[0,1,0] op_sel_hi:[1,1,1]
	v_add_f32_dpp v15, v24, v24 row_ror:8 row_mask:0xf bank_mask:0xf bound_ctrl:1
	v_add_f32_dpp v32, v25, v25 row_ror:8 row_mask:0xf bank_mask:0xf bound_ctrl:1
	ds_read_b128 v[124:127], v34 offset:19456
	v_add_f32_dpp v15, v15, v15 row_ror:4 row_mask:0xf bank_mask:0xf bound_ctrl:1
	ds_read_b128 v[128:131], v34 offset:19712
	ds_read_b128 v[132:135], v34 offset:19968
	v_add_f32_dpp v15, v15, v15 row_ror:2 row_mask:0xf bank_mask:0xf bound_ctrl:1
	ds_read_b128 v[136:139], v34 offset:20224
	ds_read_b128 v[160:163], v35 offset:80
	v_add_f32_dpp v30, v15, v15 row_ror:1 row_mask:0xf bank_mask:0xf bound_ctrl:1
	v_pk_fma_f32 v[10:11], v[96:97], v[30:31], v[16:17] op_sel_hi:[1,0,1] neg_lo:[0,1,0] neg_hi:[0,1,0]
	v_pk_fma_f32 v[8:9], v[98:99], v[30:31], v[18:19] op_sel_hi:[1,0,1] neg_lo:[0,1,0] neg_hi:[0,1,0]
	v_pk_mul_f32 v[24:25], v[10:11], v[100:101] op_sel:[0,0] op_sel_hi:[0,1]
	v_pk_fma_f32 v[24:25], v[10:11], v[102:103], v[24:25] op_sel:[1,0,0] op_sel_hi:[1,1,1]
	v_pk_fma_f32 v[24:25], v[8:9], v[104:105], v[24:25] op_sel:[0,0,0] op_sel_hi:[0,1,1]
	v_pk_fma_f32 v[24:25], v[8:9], v[106:107], v[24:25] op_sel:[1,0,0] op_sel_hi:[1,1,1]
	v_pk_fma_f32 v[16:17], v[108:109], v[158:159], v[10:11] op_sel_hi:[1,0,1]
	v_pk_fma_f32 v[18:19], v[110:111], v[158:159], v[8:9] op_sel_hi:[1,0,1]
	v_add_f32_dpp v15, v24, v24 row_ror:8 row_mask:0xf bank_mask:0xf bound_ctrl:1
	v_add_f32_dpp v33, v25, v25 row_ror:8 row_mask:0xf bank_mask:0xf bound_ctrl:1
	ds_read_b128 v[76:79], v34 offset:20480
	v_add_f32_dpp v15, v15, v15 row_ror:4 row_mask:0xf bank_mask:0xf bound_ctrl:1
	ds_read_b128 v[80:83], v34 offset:20736
	ds_read_b128 v[84:87], v34 offset:20992
	v_add_f32_dpp v15, v15, v15 row_ror:2 row_mask:0xf bank_mask:0xf bound_ctrl:1
	ds_read_b128 v[88:91], v34 offset:21248
	s_nop 0
	v_add_f32_dpp v30, v15, v15 row_ror:1 row_mask:0xf bank_mask:0xf bound_ctrl:1
	ds_write2st64_b32 v37, v32, v33 offset0:32 offset1:34
	s_waitcnt lgkmcnt(4)
	v_pk_fma_f32 v[10:11], v[112:113], v[30:31], v[16:17] op_sel_hi:[1,0,1] neg_lo:[0,1,0] neg_hi:[0,1,0]
	v_pk_fma_f32 v[8:9], v[114:115], v[30:31], v[18:19] op_sel_hi:[1,0,1] neg_lo:[0,1,0] neg_hi:[0,1,0]
	v_pk_mul_f32 v[24:25], v[10:11], v[116:117] op_sel:[0,0] op_sel_hi:[0,1]
	v_pk_fma_f32 v[24:25], v[10:11], v[118:119], v[24:25] op_sel:[1,0,0] op_sel_hi:[1,1,1]
	v_pk_fma_f32 v[24:25], v[8:9], v[120:121], v[24:25] op_sel:[0,0,0] op_sel_hi:[0,1,1]
	v_pk_fma_f32 v[24:25], v[8:9], v[122:123], v[24:25] op_sel:[1,0,0] op_sel_hi:[1,1,1]
	v_pk_fma_f32 v[16:17], v[124:125], v[158:159], v[10:11] op_sel:[0,1,0] op_sel_hi:[1,1,1]
	v_pk_fma_f32 v[18:19], v[126:127], v[158:159], v[8:9] op_sel:[0,1,0] op_sel_hi:[1,1,1]
	v_add_f32_dpp v15, v24, v24 row_ror:8 row_mask:0xf bank_mask:0xf bound_ctrl:1
	v_add_f32_dpp v32, v25, v25 row_ror:8 row_mask:0xf bank_mask:0xf bound_ctrl:1
	ds_read_b128 v[92:95], v34 offset:21504
	v_add_f32_dpp v15, v15, v15 row_ror:4 row_mask:0xf bank_mask:0xf bound_ctrl:1
	ds_read_b128 v[96:99], v34 offset:21760
	ds_read_b128 v[100:103], v34 offset:22016
	v_add_f32_dpp v15, v15, v15 row_ror:2 row_mask:0xf bank_mask:0xf bound_ctrl:1
	ds_read_b128 v[104:107], v34 offset:22272
	s_nop 0
	v_add_f32_dpp v30, v15, v15 row_ror:1 row_mask:0xf bank_mask:0xf bound_ctrl:1
	v_pk_fma_f32 v[10:11], v[128:129], v[30:31], v[16:17] op_sel_hi:[1,0,1] neg_lo:[0,1,0] neg_hi:[0,1,0]
	v_pk_fma_f32 v[8:9], v[130:131], v[30:31], v[18:19] op_sel_hi:[1,0,1] neg_lo:[0,1,0] neg_hi:[0,1,0]
	v_pk_mul_f32 v[24:25], v[10:11], v[132:133] op_sel:[0,0] op_sel_hi:[0,1]
	v_pk_fma_f32 v[24:25], v[10:11], v[134:135], v[24:25] op_sel:[1,0,0] op_sel_hi:[1,1,1]
	v_pk_fma_f32 v[24:25], v[8:9], v[136:137], v[24:25] op_sel:[0,0,0] op_sel_hi:[0,1,1]
	v_pk_fma_f32 v[24:25], v[8:9], v[138:139], v[24:25] op_sel:[1,0,0] op_sel_hi:[1,1,1]
	v_pk_fma_f32 v[16:17], v[76:77], v[160:161], v[10:11] op_sel_hi:[1,0,1]
	v_pk_fma_f32 v[18:19], v[78:79], v[160:161], v[8:9] op_sel_hi:[1,0,1]
	v_add_f32_dpp v15, v24, v24 row_ror:8 row_mask:0xf bank_mask:0xf bound_ctrl:1
	v_add_f32_dpp v33, v25, v25 row_ror:8 row_mask:0xf bank_mask:0xf bound_ctrl:1
	ds_read_b128 v[108:111], v34 offset:22528
	v_add_f32_dpp v15, v15, v15 row_ror:4 row_mask:0xf bank_mask:0xf bound_ctrl:1
	ds_read_b128 v[112:115], v34 offset:22784
	ds_read_b128 v[116:119], v34 offset:23040
	v_add_f32_dpp v15, v15, v15 row_ror:2 row_mask:0xf bank_mask:0xf bound_ctrl:1
	ds_read_b128 v[120:123], v34 offset:23296
	ds_read_b128 v[140:143], v34 offset:34304
	v_add_f32_dpp v30, v15, v15 row_ror:1 row_mask:0xf bank_mask:0xf bound_ctrl:1
	ds_write2st64_b32 v37, v32, v33 offset0:36 offset1:38
	s_waitcnt lgkmcnt(5)
	v_pk_fma_f32 v[10:11], v[80:81], v[30:31], v[16:17] op_sel_hi:[1,0,1] neg_lo:[0,1,0] neg_hi:[0,1,0]
	v_pk_fma_f32 v[8:9], v[82:83], v[30:31], v[18:19] op_sel_hi:[1,0,1] neg_lo:[0,1,0] neg_hi:[0,1,0]
	v_pk_mul_f32 v[24:25], v[10:11], v[84:85] op_sel:[0,0] op_sel_hi:[0,1]
	v_pk_fma_f32 v[24:25], v[10:11], v[86:87], v[24:25] op_sel:[1,0,0] op_sel_hi:[1,1,1]
	v_pk_fma_f32 v[24:25], v[8:9], v[88:89], v[24:25] op_sel:[0,0,0] op_sel_hi:[0,1,1]
	v_pk_fma_f32 v[24:25], v[8:9], v[90:91], v[24:25] op_sel:[1,0,0] op_sel_hi:[1,1,1]
	v_pk_fma_f32 v[16:17], v[92:93], v[160:161], v[10:11] op_sel:[0,1,0] op_sel_hi:[1,1,1]
	v_pk_fma_f32 v[18:19], v[94:95], v[160:161], v[8:9] op_sel:[0,1,0] op_sel_hi:[1,1,1]
	v_add_f32_dpp v15, v24, v24 row_ror:8 row_mask:0xf bank_mask:0xf bound_ctrl:1
	v_add_f32_dpp v32, v25, v25 row_ror:8 row_mask:0xf bank_mask:0xf bound_ctrl:1
	ds_read_b128 v[124:127], v34 offset:23552
	v_add_f32_dpp v15, v15, v15 row_ror:4 row_mask:0xf bank_mask:0xf bound_ctrl:1
	ds_read_b128 v[128:131], v34 offset:23808
	ds_read_b128 v[132:135], v34 offset:24064
	v_add_f32_dpp v15, v15, v15 row_ror:2 row_mask:0xf bank_mask:0xf bound_ctrl:1
	ds_read_b128 v[136:139], v34 offset:24320
	ds_read_b128 v[156:159], v35 offset:96
	v_add_f32_dpp v30, v15, v15 row_ror:1 row_mask:0xf bank_mask:0xf bound_ctrl:1
	v_pk_fma_f32 v[10:11], v[96:97], v[30:31], v[16:17] op_sel_hi:[1,0,1] neg_lo:[0,1,0] neg_hi:[0,1,0]
	v_pk_fma_f32 v[8:9], v[98:99], v[30:31], v[18:19] op_sel_hi:[1,0,1] neg_lo:[0,1,0] neg_hi:[0,1,0]
	v_pk_mul_f32 v[24:25], v[10:11], v[100:101] op_sel:[0,0] op_sel_hi:[0,1]
	v_pk_fma_f32 v[24:25], v[10:11], v[102:103], v[24:25] op_sel:[1,0,0] op_sel_hi:[1,1,1]
	v_pk_fma_f32 v[24:25], v[8:9], v[104:105], v[24:25] op_sel:[0,0,0] op_sel_hi:[0,1,1]
	v_pk_fma_f32 v[24:25], v[8:9], v[106:107], v[24:25] op_sel:[1,0,0] op_sel_hi:[1,1,1]
	v_pk_fma_f32 v[16:17], v[108:109], v[162:163], v[10:11] op_sel_hi:[1,0,1]
	v_pk_fma_f32 v[18:19], v[110:111], v[162:163], v[8:9] op_sel_hi:[1,0,1]
	v_add_f32_dpp v15, v24, v24 row_ror:8 row_mask:0xf bank_mask:0xf bound_ctrl:1
	v_add_f32_dpp v33, v25, v25 row_ror:8 row_mask:0xf bank_mask:0xf bound_ctrl:1
	ds_read_b128 v[76:79], v34 offset:24576
	v_add_f32_dpp v15, v15, v15 row_ror:4 row_mask:0xf bank_mask:0xf bound_ctrl:1
	ds_read_b128 v[80:83], v34 offset:24832
	ds_read_b128 v[84:87], v34 offset:25088
	v_add_f32_dpp v15, v15, v15 row_ror:2 row_mask:0xf bank_mask:0xf bound_ctrl:1
	ds_read_b128 v[88:91], v34 offset:25344
	ds_read_b128 v[144:147], v34 offset:33536
	v_add_f32_dpp v30, v15, v15 row_ror:1 row_mask:0xf bank_mask:0xf bound_ctrl:1
	ds_write2st64_b32 v37, v32, v33 offset0:40 offset1:42
	s_waitcnt lgkmcnt(5)
	v_pk_fma_f32 v[10:11], v[112:113], v[30:31], v[16:17] op_sel_hi:[1,0,1] neg_lo:[0,1,0] neg_hi:[0,1,0]
	v_pk_fma_f32 v[8:9], v[114:115], v[30:31], v[18:19] op_sel_hi:[1,0,1] neg_lo:[0,1,0] neg_hi:[0,1,0]
	v_pk_mul_f32 v[24:25], v[10:11], v[116:117] op_sel:[0,0] op_sel_hi:[0,1]
	v_pk_fma_f32 v[24:25], v[10:11], v[118:119], v[24:25] op_sel:[1,0,0] op_sel_hi:[1,1,1]
	v_pk_fma_f32 v[24:25], v[8:9], v[120:121], v[24:25] op_sel:[0,0,0] op_sel_hi:[0,1,1]
	v_pk_fma_f32 v[24:25], v[8:9], v[122:123], v[24:25] op_sel:[1,0,0] op_sel_hi:[1,1,1]
	v_pk_fma_f32 v[16:17], v[124:125], v[162:163], v[10:11] op_sel:[0,1,0] op_sel_hi:[1,1,1]
	v_pk_fma_f32 v[18:19], v[126:127], v[162:163], v[8:9] op_sel:[0,1,0] op_sel_hi:[1,1,1]
	v_add_f32_dpp v15, v24, v24 row_ror:8 row_mask:0xf bank_mask:0xf bound_ctrl:1
	v_add_f32_dpp v32, v25, v25 row_ror:8 row_mask:0xf bank_mask:0xf bound_ctrl:1
	ds_read_b128 v[92:95], v34 offset:25600
	v_add_f32_dpp v15, v15, v15 row_ror:4 row_mask:0xf bank_mask:0xf bound_ctrl:1
	ds_read_b128 v[96:99], v34 offset:25856
	ds_read_b128 v[100:103], v34 offset:26112
	v_add_f32_dpp v15, v15, v15 row_ror:2 row_mask:0xf bank_mask:0xf bound_ctrl:1
	ds_read_b128 v[104:107], v34 offset:26368
	s_nop 0
	v_add_f32_dpp v30, v15, v15 row_ror:1 row_mask:0xf bank_mask:0xf bound_ctrl:1
	v_pk_fma_f32 v[10:11], v[128:129], v[30:31], v[16:17] op_sel_hi:[1,0,1] neg_lo:[0,1,0] neg_hi:[0,1,0]
	v_pk_fma_f32 v[8:9], v[130:131], v[30:31], v[18:19] op_sel_hi:[1,0,1] neg_lo:[0,1,0] neg_hi:[0,1,0]
	v_pk_mul_f32 v[24:25], v[10:11], v[132:133] op_sel:[0,0] op_sel_hi:[0,1]
	v_pk_fma_f32 v[24:25], v[10:11], v[134:135], v[24:25] op_sel:[1,0,0] op_sel_hi:[1,1,1]
	v_pk_fma_f32 v[24:25], v[8:9], v[136:137], v[24:25] op_sel:[0,0,0] op_sel_hi:[0,1,1]
	v_pk_fma_f32 v[24:25], v[8:9], v[138:139], v[24:25] op_sel:[1,0,0] op_sel_hi:[1,1,1]
	s_nop 1
	v_add_f32_dpp v33, v25, v25 row_ror:8 row_mask:0xf bank_mask:0xf bound_ctrl:1
	ds_write2st64_b32 v37, v32, v33 offset0:44 offset1:46
	v_pk_mul_f32 v[10:11], v[10:11], v[140:141]
	v_pk_mul_f32 v[8:9], v[8:9], v[142:143]
	s_waitcnt lgkmcnt(6)
	v_pk_mul_f32 v[24:25], v[10:11], v[144:145]
	v_pk_fma_f32 v[24:25], v[8:9], v[146:147], v[24:25]
	v_add_f32_e32 v24, v24, v25
	v_pk_fma_f32 v[16:17], v[76:77], v[156:157], v[10:11] op_sel_hi:[1,0,1]
	v_pk_fma_f32 v[18:19], v[78:79], v[156:157], v[8:9] op_sel_hi:[1,0,1]
	v_add_f32_dpp v15, v24, v24 row_ror:8 row_mask:0xf bank_mask:0xf bound_ctrl:1
	ds_read_b128 v[108:111], v34 offset:26624
	ds_read_b128 v[112:115], v34 offset:26880
	v_add_f32_dpp v15, v15, v15 row_ror:4 row_mask:0xf bank_mask:0xf bound_ctrl:1
	ds_read_b128 v[116:119], v34 offset:27136
	ds_read_b128 v[120:123], v34 offset:27392
	v_add_f32_dpp v15, v15, v15 row_ror:2 row_mask:0xf bank_mask:0xf bound_ctrl:1
	s_nop 1
	v_add_f32_dpp v30, v15, v15 row_ror:1 row_mask:0xf bank_mask:0xf bound_ctrl:1
	s_waitcnt lgkmcnt(3)
	v_pk_fma_f32 v[10:11], v[80:81], v[30:31], v[16:17] op_sel_hi:[1,0,1] neg_lo:[0,1,0] neg_hi:[0,1,0]
	v_pk_fma_f32 v[8:9], v[82:83], v[30:31], v[18:19] op_sel_hi:[1,0,1] neg_lo:[0,1,0] neg_hi:[0,1,0]
	v_pk_mul_f32 v[24:25], v[10:11], v[84:85] op_sel:[0,0] op_sel_hi:[0,1]
	v_pk_fma_f32 v[24:25], v[10:11], v[86:87], v[24:25] op_sel:[1,0,0] op_sel_hi:[1,1,1]
	v_pk_fma_f32 v[24:25], v[8:9], v[88:89], v[24:25] op_sel:[0,0,0] op_sel_hi:[0,1,1]
	v_pk_fma_f32 v[24:25], v[8:9], v[90:91], v[24:25] op_sel:[1,0,0] op_sel_hi:[1,1,1]
	v_pk_fma_f32 v[16:17], v[92:93], v[156:157], v[10:11] op_sel:[0,1,0] op_sel_hi:[1,1,1]
	v_pk_fma_f32 v[18:19], v[94:95], v[156:157], v[8:9] op_sel:[0,1,0] op_sel_hi:[1,1,1]
	v_add_f32_dpp v15, v24, v24 row_ror:8 row_mask:0xf bank_mask:0xf bound_ctrl:1
	v_add_f32_dpp v32, v25, v25 row_ror:8 row_mask:0xf bank_mask:0xf bound_ctrl:1
	ds_read_b128 v[124:127], v34 offset:27648
	v_add_f32_dpp v15, v15, v15 row_ror:4 row_mask:0xf bank_mask:0xf bound_ctrl:1
	ds_read_b128 v[128:131], v34 offset:27904
	ds_read_b128 v[132:135], v34 offset:28160
	v_add_f32_dpp v15, v15, v15 row_ror:2 row_mask:0xf bank_mask:0xf bound_ctrl:1
	ds_read_b128 v[136:139], v34 offset:28416
	ds_read_b128 v[160:163], v35 offset:112
	v_add_f32_dpp v30, v15, v15 row_ror:1 row_mask:0xf bank_mask:0xf bound_ctrl:1
	v_pk_fma_f32 v[10:11], v[96:97], v[30:31], v[16:17] op_sel_hi:[1,0,1] neg_lo:[0,1,0] neg_hi:[0,1,0]
	v_pk_fma_f32 v[8:9], v[98:99], v[30:31], v[18:19] op_sel_hi:[1,0,1] neg_lo:[0,1,0] neg_hi:[0,1,0]
	v_pk_mul_f32 v[24:25], v[10:11], v[100:101] op_sel:[0,0] op_sel_hi:[0,1]
	v_pk_fma_f32 v[24:25], v[10:11], v[102:103], v[24:25] op_sel:[1,0,0] op_sel_hi:[1,1,1]
	v_pk_fma_f32 v[24:25], v[8:9], v[104:105], v[24:25] op_sel:[0,0,0] op_sel_hi:[0,1,1]
	v_pk_fma_f32 v[24:25], v[8:9], v[106:107], v[24:25] op_sel:[1,0,0] op_sel_hi:[1,1,1]
	v_pk_fma_f32 v[16:17], v[108:109], v[158:159], v[10:11] op_sel_hi:[1,0,1]
	v_pk_fma_f32 v[18:19], v[110:111], v[158:159], v[8:9] op_sel_hi:[1,0,1]
	v_add_f32_dpp v15, v24, v24 row_ror:8 row_mask:0xf bank_mask:0xf bound_ctrl:1
	v_add_f32_dpp v33, v25, v25 row_ror:8 row_mask:0xf bank_mask:0xf bound_ctrl:1
	ds_read_b128 v[76:79], v34 offset:28672
	v_add_f32_dpp v15, v15, v15 row_ror:4 row_mask:0xf bank_mask:0xf bound_ctrl:1
	ds_read_b128 v[80:83], v34 offset:28928
	ds_read_b128 v[84:87], v34 offset:29184
	v_add_f32_dpp v15, v15, v15 row_ror:2 row_mask:0xf bank_mask:0xf bound_ctrl:1
	ds_read_b128 v[88:91], v34 offset:29440
	s_nop 0
	v_add_f32_dpp v30, v15, v15 row_ror:1 row_mask:0xf bank_mask:0xf bound_ctrl:1
	ds_write2st64_b32 v37, v32, v33 offset0:48 offset1:50
	ds_read_b128 v[56:59], v52
	s_waitcnt lgkmcnt(5)
	v_pk_fma_f32 v[10:11], v[112:113], v[30:31], v[16:17] op_sel_hi:[1,0,1] neg_lo:[0,1,0] neg_hi:[0,1,0]
	v_pk_fma_f32 v[8:9], v[114:115], v[30:31], v[18:19] op_sel_hi:[1,0,1] neg_lo:[0,1,0] neg_hi:[0,1,0]
	v_pk_mul_f32 v[24:25], v[10:11], v[116:117] op_sel:[0,0] op_sel_hi:[0,1]
	v_pk_fma_f32 v[24:25], v[10:11], v[118:119], v[24:25] op_sel:[1,0,0] op_sel_hi:[1,1,1]
	v_pk_fma_f32 v[24:25], v[8:9], v[120:121], v[24:25] op_sel:[0,0,0] op_sel_hi:[0,1,1]
	v_pk_fma_f32 v[24:25], v[8:9], v[122:123], v[24:25] op_sel:[1,0,0] op_sel_hi:[1,1,1]
	v_pk_fma_f32 v[16:17], v[124:125], v[158:159], v[10:11] op_sel:[0,1,0] op_sel_hi:[1,1,1]
	v_pk_fma_f32 v[18:19], v[126:127], v[158:159], v[8:9] op_sel:[0,1,0] op_sel_hi:[1,1,1]
	v_add_f32_dpp v15, v24, v24 row_ror:8 row_mask:0xf bank_mask:0xf bound_ctrl:1
	v_add_f32_dpp v32, v25, v25 row_ror:8 row_mask:0xf bank_mask:0xf bound_ctrl:1
	ds_read_b128 v[92:95], v34 offset:29696
	v_add_f32_dpp v15, v15, v15 row_ror:4 row_mask:0xf bank_mask:0xf bound_ctrl:1
	ds_read_b128 v[96:99], v34 offset:29952
	ds_read_b128 v[100:103], v34 offset:30208
	v_add_f32_dpp v15, v15, v15 row_ror:2 row_mask:0xf bank_mask:0xf bound_ctrl:1
	ds_read_b128 v[104:107], v34 offset:30464
	s_nop 0
	v_add_f32_dpp v30, v15, v15 row_ror:1 row_mask:0xf bank_mask:0xf bound_ctrl:1
	s_waitcnt lgkmcnt(4)
	v_min_u32_e32 v56, v56, v57
	v_min3_u32 v56, v56, v58, v59
	v_pk_fma_f32 v[10:11], v[128:129], v[30:31], v[16:17] op_sel_hi:[1,0,1] neg_lo:[0,1,0] neg_hi:[0,1,0]
	v_pk_fma_f32 v[8:9], v[130:131], v[30:31], v[18:19] op_sel_hi:[1,0,1] neg_lo:[0,1,0] neg_hi:[0,1,0]
	v_pk_mul_f32 v[24:25], v[10:11], v[132:133] op_sel:[0,0] op_sel_hi:[0,1]
	v_pk_fma_f32 v[24:25], v[10:11], v[134:135], v[24:25] op_sel:[1,0,0] op_sel_hi:[1,1,1]
	v_pk_fma_f32 v[24:25], v[8:9], v[136:137], v[24:25] op_sel:[0,0,0] op_sel_hi:[0,1,1]
	v_pk_fma_f32 v[24:25], v[8:9], v[138:139], v[24:25] op_sel:[1,0,0] op_sel_hi:[1,1,1]
	v_pk_fma_f32 v[16:17], v[76:77], v[160:161], v[10:11] op_sel_hi:[1,0,1]
	v_pk_fma_f32 v[18:19], v[78:79], v[160:161], v[8:9] op_sel_hi:[1,0,1]
	v_add_f32_dpp v15, v24, v24 row_ror:8 row_mask:0xf bank_mask:0xf bound_ctrl:1
	v_add_f32_dpp v33, v25, v25 row_ror:8 row_mask:0xf bank_mask:0xf bound_ctrl:1
	ds_read_b128 v[108:111], v34 offset:30720
	v_add_f32_dpp v15, v15, v15 row_ror:4 row_mask:0xf bank_mask:0xf bound_ctrl:1
	ds_read_b128 v[112:115], v34 offset:30976
	ds_read_b128 v[116:119], v34 offset:31232
	v_add_f32_dpp v15, v15, v15 row_ror:2 row_mask:0xf bank_mask:0xf bound_ctrl:1
	ds_read_b128 v[120:123], v34 offset:31488
	ds_read_b128 v[140:143], v34 offset:34560
	v_add_f32_dpp v30, v15, v15 row_ror:1 row_mask:0xf bank_mask:0xf bound_ctrl:1
	ds_write2st64_b32 v37, v32, v33 offset0:52 offset1:54
	s_waitcnt lgkmcnt(5)
	v_pk_fma_f32 v[10:11], v[80:81], v[30:31], v[16:17] op_sel_hi:[1,0,1] neg_lo:[0,1,0] neg_hi:[0,1,0]
	v_pk_fma_f32 v[8:9], v[82:83], v[30:31], v[18:19] op_sel_hi:[1,0,1] neg_lo:[0,1,0] neg_hi:[0,1,0]
	v_pk_mul_f32 v[24:25], v[10:11], v[84:85] op_sel:[0,0] op_sel_hi:[0,1]
	v_pk_fma_f32 v[24:25], v[10:11], v[86:87], v[24:25] op_sel:[1,0,0] op_sel_hi:[1,1,1]
	v_pk_fma_f32 v[24:25], v[8:9], v[88:89], v[24:25] op_sel:[0,0,0] op_sel_hi:[0,1,1]
	v_pk_fma_f32 v[24:25], v[8:9], v[90:91], v[24:25] op_sel:[1,0,0] op_sel_hi:[1,1,1]
	v_pk_fma_f32 v[16:17], v[92:93], v[160:161], v[10:11] op_sel:[0,1,0] op_sel_hi:[1,1,1]
	v_pk_fma_f32 v[18:19], v[94:95], v[160:161], v[8:9] op_sel:[0,1,0] op_sel_hi:[1,1,1]
	v_add_f32_dpp v15, v24, v24 row_ror:8 row_mask:0xf bank_mask:0xf bound_ctrl:1
	v_add_f32_dpp v32, v25, v25 row_ror:8 row_mask:0xf bank_mask:0xf bound_ctrl:1
	ds_read_b128 v[124:127], v34 offset:31744
	v_add_f32_dpp v15, v15, v15 row_ror:4 row_mask:0xf bank_mask:0xf bound_ctrl:1
	ds_read_b128 v[128:131], v34 offset:32000
	ds_read_b128 v[132:135], v34 offset:32256
	v_add_f32_dpp v15, v15, v15 row_ror:2 row_mask:0xf bank_mask:0xf bound_ctrl:1
	ds_read_b128 v[136:139], v34 offset:32512
	s_nop 0
	v_add_f32_dpp v30, v15, v15 row_ror:1 row_mask:0xf bank_mask:0xf bound_ctrl:1
	v_readfirstlane_b32 s54, v56
	s_add_u32 s64, s6, 2
	s_cmp_lt_u32 s54, s64
	s_cbranch_scc1 .Lss_spin_0
.Lss_ok_0:
	v_pk_fma_f32 v[10:11], v[96:97], v[30:31], v[16:17] op_sel_hi:[1,0,1] neg_lo:[0,1,0] neg_hi:[0,1,0]
	v_pk_fma_f32 v[8:9], v[98:99], v[30:31], v[18:19] op_sel_hi:[1,0,1] neg_lo:[0,1,0] neg_hi:[0,1,0]
	v_pk_mul_f32 v[24:25], v[10:11], v[100:101] op_sel:[0,0] op_sel_hi:[0,1]
	v_pk_fma_f32 v[24:25], v[10:11], v[102:103], v[24:25] op_sel:[1,0,0] op_sel_hi:[1,1,1]
	v_pk_fma_f32 v[24:25], v[8:9], v[104:105], v[24:25] op_sel:[0,0,0] op_sel_hi:[0,1,1]
	v_pk_fma_f32 v[24:25], v[8:9], v[106:107], v[24:25] op_sel:[1,0,0] op_sel_hi:[1,1,1]
	v_pk_fma_f32 v[16:17], v[108:109], v[162:163], v[10:11] op_sel_hi:[1,0,1]
	v_pk_fma_f32 v[18:19], v[110:111], v[162:163], v[8:9] op_sel_hi:[1,0,1]
	v_add_f32_dpp v15, v24, v24 row_ror:8 row_mask:0xf bank_mask:0xf bound_ctrl:1
	v_add_f32_dpp v33, v25, v25 row_ror:8 row_mask:0xf bank_mask:0xf bound_ctrl:1
	ds_read_b128 v[76:79], v48 offset:0
	v_add_f32_dpp v15, v15, v15 row_ror:4 row_mask:0xf bank_mask:0xf bound_ctrl:1
	ds_read_b128 v[80:83], v48 offset:256
	ds_read_b128 v[84:87], v48 offset:512
	v_add_f32_dpp v15, v15, v15 row_ror:2 row_mask:0xf bank_mask:0xf bound_ctrl:1
	ds_read_b128 v[88:91], v48 offset:768
	ds_read_b128 v[144:147], v48 offset:32768
	v_add_f32_dpp v30, v15, v15 row_ror:1 row_mask:0xf bank_mask:0xf bound_ctrl:1
	ds_write2st64_b32 v37, v32, v33 offset0:56 offset1:58
	ds_read_b128 v[156:159], v49 offset:0
	s_waitcnt lgkmcnt(6)
	v_pk_fma_f32 v[10:11], v[112:113], v[30:31], v[16:17] op_sel_hi:[1,0,1] neg_lo:[0,1,0] neg_hi:[0,1,0]
	v_pk_fma_f32 v[8:9], v[114:115], v[30:31], v[18:19] op_sel_hi:[1,0,1] neg_lo:[0,1,0] neg_hi:[0,1,0]
	v_pk_mul_f32 v[24:25], v[10:11], v[116:117] op_sel:[0,0] op_sel_hi:[0,1]
	v_pk_fma_f32 v[24:25], v[10:11], v[118:119], v[24:25] op_sel:[1,0,0] op_sel_hi:[1,1,1]
	v_pk_fma_f32 v[24:25], v[8:9], v[120:121], v[24:25] op_sel:[0,0,0] op_sel_hi:[0,1,1]
	v_pk_fma_f32 v[24:25], v[8:9], v[122:123], v[24:25] op_sel:[1,0,0] op_sel_hi:[1,1,1]
	v_pk_fma_f32 v[16:17], v[124:125], v[162:163], v[10:11] op_sel:[0,1,0] op_sel_hi:[1,1,1]
	v_pk_fma_f32 v[18:19], v[126:127], v[162:163], v[8:9] op_sel:[0,1,0] op_sel_hi:[1,1,1]
	v_add_f32_dpp v15, v24, v24 row_ror:8 row_mask:0xf bank_mask:0xf bound_ctrl:1
	v_add_f32_dpp v32, v25, v25 row_ror:8 row_mask:0xf bank_mask:0xf bound_ctrl:1
	ds_read_b128 v[92:95], v48 offset:1024
	v_add_f32_dpp v15, v15, v15 row_ror:4 row_mask:0xf bank_mask:0xf bound_ctrl:1
	ds_read_b128 v[96:99], v48 offset:1280
	ds_read_b128 v[100:103], v48 offset:1536
	v_add_f32_dpp v15, v15, v15 row_ror:2 row_mask:0xf bank_mask:0xf bound_ctrl:1
	ds_read_b128 v[104:107], v48 offset:1792
	s_nop 0
	v_add_f32_dpp v30, v15, v15 row_ror:1 row_mask:0xf bank_mask:0xf bound_ctrl:1
	v_pk_fma_f32 v[10:11], v[128:129], v[30:31], v[16:17] op_sel_hi:[1,0,1] neg_lo:[0,1,0] neg_hi:[0,1,0]
	v_pk_fma_f32 v[8:9], v[130:131], v[30:31], v[18:19] op_sel_hi:[1,0,1] neg_lo:[0,1,0] neg_hi:[0,1,0]
	v_pk_mul_f32 v[24:25], v[10:11], v[132:133] op_sel:[0,0] op_sel_hi:[0,1]
	v_pk_fma_f32 v[24:25], v[10:11], v[134:135], v[24:25] op_sel:[1,0,0] op_sel_hi:[1,1,1]
	v_pk_fma_f32 v[24:25], v[8:9], v[136:137], v[24:25] op_sel:[0,0,0] op_sel_hi:[0,1,1]
	v_pk_fma_f32 v[24:25], v[8:9], v[138:139], v[24:25] op_sel:[1,0,0] op_sel_hi:[1,1,1]
	s_nop 1
	v_add_f32_dpp v33, v25, v25 row_ror:8 row_mask:0xf bank_mask:0xf bound_ctrl:1
	ds_write2st64_b32 v37, v32, v33 offset0:60 offset1:62
	v_pk_mul_f32 v[10:11], v[10:11], v[140:141]
	v_pk_mul_f32 v[8:9], v[8:9], v[142:143]
	s_waitcnt lgkmcnt(7)
	v_pk_mul_f32 v[24:25], v[10:11], v[144:145]
	v_pk_fma_f32 v[24:25], v[8:9], v[146:147], v[24:25]
	v_add_f32_e32 v24, v24, v25
	s_waitcnt lgkmcnt(5)
	v_pk_fma_f32 v[16:17], v[76:77], v[156:157], v[10:11] op_sel_hi:[1,0,1]
	v_pk_fma_f32 v[18:19], v[78:79], v[156:157], v[8:9] op_sel_hi:[1,0,1]
	v_add_f32_dpp v15, v24, v24 row_ror:8 row_mask:0xf bank_mask:0xf bound_ctrl:1
	v_add_u32_e32 v51, 1, v51
	s_add_u32 s6, s6, 1
	v_add_f32_dpp v15, v15, v15 row_ror:4 row_mask:0xf bank_mask:0xf bound_ctrl:1
	ds_write_b32 v53, v51
	ds_read_b128 v[108:111], v48 offset:2048
	v_add_f32_dpp v15, v15, v15 row_ror:2 row_mask:0xf bank_mask:0xf bound_ctrl:1
	ds_read_b128 v[112:115], v48 offset:2304
	ds_read_b128 v[116:119], v48 offset:2560
	v_add_f32_dpp v30, v15, v15 row_ror:1 row_mask:0xf bank_mask:0xf bound_ctrl:1
	ds_read_b128 v[120:123], v48 offset:2816
	s_waitcnt lgkmcnt(3)
	v_pk_fma_f32 v[10:11], v[80:81], v[30:31], v[16:17] op_sel_hi:[1,0,1] neg_lo:[0,1,0] neg_hi:[0,1,0]
	v_pk_fma_f32 v[8:9], v[82:83], v[30:31], v[18:19] op_sel_hi:[1,0,1] neg_lo:[0,1,0] neg_hi:[0,1,0]
	v_pk_mul_f32 v[24:25], v[10:11], v[84:85] op_sel:[0,0] op_sel_hi:[0,1]
	v_pk_fma_f32 v[24:25], v[10:11], v[86:87], v[24:25] op_sel:[1,0,0] op_sel_hi:[1,1,1]
	v_pk_fma_f32 v[24:25], v[8:9], v[88:89], v[24:25] op_sel:[0,0,0] op_sel_hi:[0,1,1]
	v_pk_fma_f32 v[24:25], v[8:9], v[90:91], v[24:25] op_sel:[1,0,0] op_sel_hi:[1,1,1]
	v_pk_fma_f32 v[16:17], v[92:93], v[156:157], v[10:11] op_sel:[0,1,0] op_sel_hi:[1,1,1]
	v_pk_fma_f32 v[18:19], v[94:95], v[156:157], v[8:9] op_sel:[0,1,0] op_sel_hi:[1,1,1]
	v_add_f32_dpp v15, v24, v24 row_ror:8 row_mask:0xf bank_mask:0xf bound_ctrl:1
	v_add_f32_dpp v32, v25, v25 row_ror:8 row_mask:0xf bank_mask:0xf bound_ctrl:1
	ds_read_b128 v[124:127], v48 offset:3072
	v_add_f32_dpp v15, v15, v15 row_ror:4 row_mask:0xf bank_mask:0xf bound_ctrl:1
	ds_read_b128 v[128:131], v48 offset:3328
	ds_read_b128 v[132:135], v48 offset:3584
	v_add_f32_dpp v15, v15, v15 row_ror:2 row_mask:0xf bank_mask:0xf bound_ctrl:1
	ds_read_b128 v[136:139], v48 offset:3840
	ds_read_b128 v[160:163], v49 offset:16
	v_add_f32_dpp v30, v15, v15 row_ror:1 row_mask:0xf bank_mask:0xf bound_ctrl:1
	v_pk_fma_f32 v[10:11], v[96:97], v[30:31], v[16:17] op_sel_hi:[1,0,1] neg_lo:[0,1,0] neg_hi:[0,1,0]
	v_pk_fma_f32 v[8:9], v[98:99], v[30:31], v[18:19] op_sel_hi:[1,0,1] neg_lo:[0,1,0] neg_hi:[0,1,0]
	v_pk_mul_f32 v[24:25], v[10:11], v[100:101] op_sel:[0,0] op_sel_hi:[0,1]
	v_pk_fma_f32 v[24:25], v[10:11], v[102:103], v[24:25] op_sel:[1,0,0] op_sel_hi:[1,1,1]
	v_pk_fma_f32 v[24:25], v[8:9], v[104:105], v[24:25] op_sel:[0,0,0] op_sel_hi:[0,1,1]
	v_pk_fma_f32 v[24:25], v[8:9], v[106:107], v[24:25] op_sel:[1,0,0] op_sel_hi:[1,1,1]
	v_pk_fma_f32 v[16:17], v[108:109], v[158:159], v[10:11] op_sel_hi:[1,0,1]
	v_pk_fma_f32 v[18:19], v[110:111], v[158:159], v[8:9] op_sel_hi:[1,0,1]
	v_add_f32_dpp v15, v24, v24 row_ror:8 row_mask:0xf bank_mask:0xf bound_ctrl:1
	v_add_f32_dpp v33, v25, v25 row_ror:8 row_mask:0xf bank_mask:0xf bound_ctrl:1
	ds_read_b128 v[76:79], v48 offset:4096
	v_add_f32_dpp v15, v15, v15 row_ror:4 row_mask:0xf bank_mask:0xf bound_ctrl:1
	ds_read_b128 v[80:83], v48 offset:4352
	ds_read_b128 v[84:87], v48 offset:4608
	v_add_f32_dpp v15, v15, v15 row_ror:2 row_mask:0xf bank_mask:0xf bound_ctrl:1
	ds_read_b128 v[88:91], v48 offset:4864
	s_nop 0
	v_add_f32_dpp v30, v15, v15 row_ror:1 row_mask:0xf bank_mask:0xf bound_ctrl:1
	ds_write2st64_b32 v50, v32, v33 offset0:0 offset1:2
	s_waitcnt lgkmcnt(4)
	v_pk_fma_f32 v[10:11], v[112:113], v[30:31], v[16:17] op_sel_hi:[1,0,1] neg_lo:[0,1,0] neg_hi:[0,1,0]
	v_pk_fma_f32 v[8:9], v[114:115], v[30:31], v[18:19] op_sel_hi:[1,0,1] neg_lo:[0,1,0] neg_hi:[0,1,0]
	v_pk_mul_f32 v[24:25], v[10:11], v[116:117] op_sel:[0,0] op_sel_hi:[0,1]
	v_pk_fma_f32 v[24:25], v[10:11], v[118:119], v[24:25] op_sel:[1,0,0] op_sel_hi:[1,1,1]
	v_pk_fma_f32 v[24:25], v[8:9], v[120:121], v[24:25] op_sel:[0,0,0] op_sel_hi:[0,1,1]
	v_pk_fma_f32 v[24:25], v[8:9], v[122:123], v[24:25] op_sel:[1,0,0] op_sel_hi:[1,1,1]
	v_pk_fma_f32 v[16:17], v[124:125], v[158:159], v[10:11] op_sel:[0,1,0] op_sel_hi:[1,1,1]
	v_pk_fma_f32 v[18:19], v[126:127], v[158:159], v[8:9] op_sel:[0,1,0] op_sel_hi:[1,1,1]
	v_add_f32_dpp v15, v24, v24 row_ror:8 row_mask:0xf bank_mask:0xf bound_ctrl:1
	v_add_f32_dpp v32, v25, v25 row_ror:8 row_mask:0xf bank_mask:0xf bound_ctrl:1
	ds_read_b128 v[92:95], v48 offset:5120
	v_add_f32_dpp v15, v15, v15 row_ror:4 row_mask:0xf bank_mask:0xf bound_ctrl:1
	ds_read_b128 v[96:99], v48 offset:5376
	ds_read_b128 v[100:103], v48 offset:5632
	v_add_f32_dpp v15, v15, v15 row_ror:2 row_mask:0xf bank_mask:0xf bound_ctrl:1
	ds_read_b128 v[104:107], v48 offset:5888
	s_nop 0
	v_add_f32_dpp v30, v15, v15 row_ror:1 row_mask:0xf bank_mask:0xf bound_ctrl:1
	v_pk_fma_f32 v[10:11], v[128:129], v[30:31], v[16:17] op_sel_hi:[1,0,1] neg_lo:[0,1,0] neg_hi:[0,1,0]
	v_pk_fma_f32 v[8:9], v[130:131], v[30:31], v[18:19] op_sel_hi:[1,0,1] neg_lo:[0,1,0] neg_hi:[0,1,0]
	v_pk_mul_f32 v[24:25], v[10:11], v[132:133] op_sel:[0,0] op_sel_hi:[0,1]
	v_pk_fma_f32 v[24:25], v[10:11], v[134:135], v[24:25] op_sel:[1,0,0] op_sel_hi:[1,1,1]
	v_pk_fma_f32 v[24:25], v[8:9], v[136:137], v[24:25] op_sel:[0,0,0] op_sel_hi:[0,1,1]
	v_pk_fma_f32 v[24:25], v[8:9], v[138:139], v[24:25] op_sel:[1,0,0] op_sel_hi:[1,1,1]
	v_pk_fma_f32 v[16:17], v[76:77], v[160:161], v[10:11] op_sel_hi:[1,0,1]
	v_pk_fma_f32 v[18:19], v[78:79], v[160:161], v[8:9] op_sel_hi:[1,0,1]
	v_add_f32_dpp v15, v24, v24 row_ror:8 row_mask:0xf bank_mask:0xf bound_ctrl:1
	v_add_f32_dpp v33, v25, v25 row_ror:8 row_mask:0xf bank_mask:0xf bound_ctrl:1
	ds_read_b128 v[108:111], v48 offset:6144
	v_add_f32_dpp v15, v15, v15 row_ror:4 row_mask:0xf bank_mask:0xf bound_ctrl:1
	ds_read_b128 v[112:115], v48 offset:6400
	ds_read_b128 v[116:119], v48 offset:6656
	v_add_f32_dpp v15, v15, v15 row_ror:2 row_mask:0xf bank_mask:0xf bound_ctrl:1
	ds_read_b128 v[120:123], v48 offset:6912
	ds_read_b128 v[140:143], v48 offset:33792
	v_add_f32_dpp v30, v15, v15 row_ror:1 row_mask:0xf bank_mask:0xf bound_ctrl:1
	ds_write2st64_b32 v50, v32, v33 offset0:4 offset1:6
	s_waitcnt lgkmcnt(5)
	v_pk_fma_f32 v[10:11], v[80:81], v[30:31], v[16:17] op_sel_hi:[1,0,1] neg_lo:[0,1,0] neg_hi:[0,1,0]
	v_pk_fma_f32 v[8:9], v[82:83], v[30:31], v[18:19] op_sel_hi:[1,0,1] neg_lo:[0,1,0] neg_hi:[0,1,0]
	v_pk_mul_f32 v[24:25], v[10:11], v[84:85] op_sel:[0,0] op_sel_hi:[0,1]
	v_pk_fma_f32 v[24:25], v[10:11], v[86:87], v[24:25] op_sel:[1,0,0] op_sel_hi:[1,1,1]
	v_pk_fma_f32 v[24:25], v[8:9], v[88:89], v[24:25] op_sel:[0,0,0] op_sel_hi:[0,1,1]
	v_pk_fma_f32 v[24:25], v[8:9], v[90:91], v[24:25] op_sel:[1,0,0] op_sel_hi:[1,1,1]
	v_pk_fma_f32 v[16:17], v[92:93], v[160:161], v[10:11] op_sel:[0,1,0] op_sel_hi:[1,1,1]
	v_pk_fma_f32 v[18:19], v[94:95], v[160:161], v[8:9] op_sel:[0,1,0] op_sel_hi:[1,1,1]
	v_add_f32_dpp v15, v24, v24 row_ror:8 row_mask:0xf bank_mask:0xf bound_ctrl:1
	v_add_f32_dpp v32, v25, v25 row_ror:8 row_mask:0xf bank_mask:0xf bound_ctrl:1
	ds_read_b128 v[124:127], v48 offset:7168
	v_add_f32_dpp v15, v15, v15 row_ror:4 row_mask:0xf bank_mask:0xf bound_ctrl:1
	ds_read_b128 v[128:131], v48 offset:7424
	ds_read_b128 v[132:135], v48 offset:7680
	v_add_f32_dpp v15, v15, v15 row_ror:2 row_mask:0xf bank_mask:0xf bound_ctrl:1
	ds_read_b128 v[136:139], v48 offset:7936
	ds_read_b128 v[156:159], v49 offset:32
	v_add_f32_dpp v30, v15, v15 row_ror:1 row_mask:0xf bank_mask:0xf bound_ctrl:1
	v_pk_fma_f32 v[10:11], v[96:97], v[30:31], v[16:17] op_sel_hi:[1,0,1] neg_lo:[0,1,0] neg_hi:[0,1,0]
	v_pk_fma_f32 v[8:9], v[98:99], v[30:31], v[18:19] op_sel_hi:[1,0,1] neg_lo:[0,1,0] neg_hi:[0,1,0]
	v_pk_mul_f32 v[24:25], v[10:11], v[100:101] op_sel:[0,0] op_sel_hi:[0,1]
	v_pk_fma_f32 v[24:25], v[10:11], v[102:103], v[24:25] op_sel:[1,0,0] op_sel_hi:[1,1,1]
	v_pk_fma_f32 v[24:25], v[8:9], v[104:105], v[24:25] op_sel:[0,0,0] op_sel_hi:[0,1,1]
	v_pk_fma_f32 v[24:25], v[8:9], v[106:107], v[24:25] op_sel:[1,0,0] op_sel_hi:[1,1,1]
	v_pk_fma_f32 v[16:17], v[108:109], v[162:163], v[10:11] op_sel_hi:[1,0,1]
	v_pk_fma_f32 v[18:19], v[110:111], v[162:163], v[8:9] op_sel_hi:[1,0,1]
	v_add_f32_dpp v15, v24, v24 row_ror:8 row_mask:0xf bank_mask:0xf bound_ctrl:1
	v_add_f32_dpp v33, v25, v25 row_ror:8 row_mask:0xf bank_mask:0xf bound_ctrl:1
	ds_read_b128 v[76:79], v48 offset:8192
	v_add_f32_dpp v15, v15, v15 row_ror:4 row_mask:0xf bank_mask:0xf bound_ctrl:1
	ds_read_b128 v[80:83], v48 offset:8448
	ds_read_b128 v[84:87], v48 offset:8704
	v_add_f32_dpp v15, v15, v15 row_ror:2 row_mask:0xf bank_mask:0xf bound_ctrl:1
	ds_read_b128 v[88:91], v48 offset:8960
	ds_read_b128 v[144:147], v48 offset:33024
	v_add_f32_dpp v30, v15, v15 row_ror:1 row_mask:0xf bank_mask:0xf bound_ctrl:1
	ds_write2st64_b32 v50, v32, v33 offset0:8 offset1:10
	s_waitcnt lgkmcnt(5)
	v_pk_fma_f32 v[10:11], v[112:113], v[30:31], v[16:17] op_sel_hi:[1,0,1] neg_lo:[0,1,0] neg_hi:[0,1,0]
	v_pk_fma_f32 v[8:9], v[114:115], v[30:31], v[18:19] op_sel_hi:[1,0,1] neg_lo:[0,1,0] neg_hi:[0,1,0]
	v_pk_mul_f32 v[24:25], v[10:11], v[116:117] op_sel:[0,0] op_sel_hi:[0,1]
	v_pk_fma_f32 v[24:25], v[10:11], v[118:119], v[24:25] op_sel:[1,0,0] op_sel_hi:[1,1,1]
	v_pk_fma_f32 v[24:25], v[8:9], v[120:121], v[24:25] op_sel:[0,0,0] op_sel_hi:[0,1,1]
	v_pk_fma_f32 v[24:25], v[8:9], v[122:123], v[24:25] op_sel:[1,0,0] op_sel_hi:[1,1,1]
	v_pk_fma_f32 v[16:17], v[124:125], v[162:163], v[10:11] op_sel:[0,1,0] op_sel_hi:[1,1,1]
	v_pk_fma_f32 v[18:19], v[126:127], v[162:163], v[8:9] op_sel:[0,1,0] op_sel_hi:[1,1,1]
	v_add_f32_dpp v15, v24, v24 row_ror:8 row_mask:0xf bank_mask:0xf bound_ctrl:1
	v_add_f32_dpp v32, v25, v25 row_ror:8 row_mask:0xf bank_mask:0xf bound_ctrl:1
	ds_read_b128 v[92:95], v48 offset:9216
	v_add_f32_dpp v15, v15, v15 row_ror:4 row_mask:0xf bank_mask:0xf bound_ctrl:1
	ds_read_b128 v[96:99], v48 offset:9472
	ds_read_b128 v[100:103], v48 offset:9728
	v_add_f32_dpp v15, v15, v15 row_ror:2 row_mask:0xf bank_mask:0xf bound_ctrl:1
	ds_read_b128 v[104:107], v48 offset:9984
	s_nop 0
	v_add_f32_dpp v30, v15, v15 row_ror:1 row_mask:0xf bank_mask:0xf bound_ctrl:1
	v_pk_fma_f32 v[10:11], v[128:129], v[30:31], v[16:17] op_sel_hi:[1,0,1] neg_lo:[0,1,0] neg_hi:[0,1,0]
	v_pk_fma_f32 v[8:9], v[130:131], v[30:31], v[18:19] op_sel_hi:[1,0,1] neg_lo:[0,1,0] neg_hi:[0,1,0]
	v_pk_mul_f32 v[24:25], v[10:11], v[132:133] op_sel:[0,0] op_sel_hi:[0,1]
	v_pk_fma_f32 v[24:25], v[10:11], v[134:135], v[24:25] op_sel:[1,0,0] op_sel_hi:[1,1,1]
	v_pk_fma_f32 v[24:25], v[8:9], v[136:137], v[24:25] op_sel:[0,0,0] op_sel_hi:[0,1,1]
	v_pk_fma_f32 v[24:25], v[8:9], v[138:139], v[24:25] op_sel:[1,0,0] op_sel_hi:[1,1,1]
	s_nop 1
	v_add_f32_dpp v33, v25, v25 row_ror:8 row_mask:0xf bank_mask:0xf bound_ctrl:1
	ds_write2st64_b32 v50, v32, v33 offset0:12 offset1:14
	v_pk_mul_f32 v[10:11], v[10:11], v[140:141]
	v_pk_mul_f32 v[8:9], v[8:9], v[142:143]
	s_waitcnt lgkmcnt(6)
	v_pk_mul_f32 v[24:25], v[10:11], v[144:145]
	v_pk_fma_f32 v[24:25], v[8:9], v[146:147], v[24:25]
	v_add_f32_e32 v24, v24, v25
	v_pk_fma_f32 v[16:17], v[76:77], v[156:157], v[10:11] op_sel_hi:[1,0,1]
	v_pk_fma_f32 v[18:19], v[78:79], v[156:157], v[8:9] op_sel_hi:[1,0,1]
	v_add_f32_dpp v15, v24, v24 row_ror:8 row_mask:0xf bank_mask:0xf bound_ctrl:1
	ds_read_b128 v[108:111], v48 offset:10240
	ds_read_b128 v[112:115], v48 offset:10496
	v_add_f32_dpp v15, v15, v15 row_ror:4 row_mask:0xf bank_mask:0xf bound_ctrl:1
	ds_read_b128 v[116:119], v48 offset:10752
	ds_read_b128 v[120:123], v48 offset:11008
	v_add_f32_dpp v15, v15, v15 row_ror:2 row_mask:0xf bank_mask:0xf bound_ctrl:1
	s_nop 1
	v_add_f32_dpp v30, v15, v15 row_ror:1 row_mask:0xf bank_mask:0xf bound_ctrl:1
	s_waitcnt lgkmcnt(3)
	v_pk_fma_f32 v[10:11], v[80:81], v[30:31], v[16:17] op_sel_hi:[1,0,1] neg_lo:[0,1,0] neg_hi:[0,1,0]
	v_pk_fma_f32 v[8:9], v[82:83], v[30:31], v[18:19] op_sel_hi:[1,0,1] neg_lo:[0,1,0] neg_hi:[0,1,0]
	v_pk_mul_f32 v[24:25], v[10:11], v[84:85] op_sel:[0,0] op_sel_hi:[0,1]
	v_pk_fma_f32 v[24:25], v[10:11], v[86:87], v[24:25] op_sel:[1,0,0] op_sel_hi:[1,1,1]
	v_pk_fma_f32 v[24:25], v[8:9], v[88:89], v[24:25] op_sel:[0,0,0] op_sel_hi:[0,1,1]
	v_pk_fma_f32 v[24:25], v[8:9], v[90:91], v[24:25] op_sel:[1,0,0] op_sel_hi:[1,1,1]
	v_pk_fma_f32 v[16:17], v[92:93], v[156:157], v[10:11] op_sel:[0,1,0] op_sel_hi:[1,1,1]
	v_pk_fma_f32 v[18:19], v[94:95], v[156:157], v[8:9] op_sel:[0,1,0] op_sel_hi:[1,1,1]
	v_add_f32_dpp v15, v24, v24 row_ror:8 row_mask:0xf bank_mask:0xf bound_ctrl:1
	v_add_f32_dpp v32, v25, v25 row_ror:8 row_mask:0xf bank_mask:0xf bound_ctrl:1
	ds_read_b128 v[124:127], v48 offset:11264
	v_add_f32_dpp v15, v15, v15 row_ror:4 row_mask:0xf bank_mask:0xf bound_ctrl:1
	ds_read_b128 v[128:131], v48 offset:11520
	ds_read_b128 v[132:135], v48 offset:11776
	v_add_f32_dpp v15, v15, v15 row_ror:2 row_mask:0xf bank_mask:0xf bound_ctrl:1
	ds_read_b128 v[136:139], v48 offset:12032
	ds_read_b128 v[160:163], v49 offset:48
	v_add_f32_dpp v30, v15, v15 row_ror:1 row_mask:0xf bank_mask:0xf bound_ctrl:1
	v_pk_fma_f32 v[10:11], v[96:97], v[30:31], v[16:17] op_sel_hi:[1,0,1] neg_lo:[0,1,0] neg_hi:[0,1,0]
	v_pk_fma_f32 v[8:9], v[98:99], v[30:31], v[18:19] op_sel_hi:[1,0,1] neg_lo:[0,1,0] neg_hi:[0,1,0]
	v_pk_mul_f32 v[24:25], v[10:11], v[100:101] op_sel:[0,0] op_sel_hi:[0,1]
	v_pk_fma_f32 v[24:25], v[10:11], v[102:103], v[24:25] op_sel:[1,0,0] op_sel_hi:[1,1,1]
	v_pk_fma_f32 v[24:25], v[8:9], v[104:105], v[24:25] op_sel:[0,0,0] op_sel_hi:[0,1,1]
	v_pk_fma_f32 v[24:25], v[8:9], v[106:107], v[24:25] op_sel:[1,0,0] op_sel_hi:[1,1,1]
	v_pk_fma_f32 v[16:17], v[108:109], v[158:159], v[10:11] op_sel_hi:[1,0,1]
	v_pk_fma_f32 v[18:19], v[110:111], v[158:159], v[8:9] op_sel_hi:[1,0,1]
	v_add_f32_dpp v15, v24, v24 row_ror:8 row_mask:0xf bank_mask:0xf bound_ctrl:1
	v_add_f32_dpp v33, v25, v25 row_ror:8 row_mask:0xf bank_mask:0xf bound_ctrl:1
	ds_read_b128 v[76:79], v48 offset:12288
	v_add_f32_dpp v15, v15, v15 row_ror:4 row_mask:0xf bank_mask:0xf bound_ctrl:1
	ds_read_b128 v[80:83], v48 offset:12544
	ds_read_b128 v[84:87], v48 offset:12800
	v_add_f32_dpp v15, v15, v15 row_ror:2 row_mask:0xf bank_mask:0xf bound_ctrl:1
	ds_read_b128 v[88:91], v48 offset:13056
	s_nop 0
	v_add_f32_dpp v30, v15, v15 row_ror:1 row_mask:0xf bank_mask:0xf bound_ctrl:1
	ds_write2st64_b32 v50, v32, v33 offset0:16 offset1:18
	s_waitcnt lgkmcnt(4)
	v_pk_fma_f32 v[10:11], v[112:113], v[30:31], v[16:17] op_sel_hi:[1,0,1] neg_lo:[0,1,0] neg_hi:[0,1,0]
	v_pk_fma_f32 v[8:9], v[114:115], v[30:31], v[18:19] op_sel_hi:[1,0,1] neg_lo:[0,1,0] neg_hi:[0,1,0]
	v_pk_mul_f32 v[24:25], v[10:11], v[116:117] op_sel:[0,0] op_sel_hi:[0,1]
	v_pk_fma_f32 v[24:25], v[10:11], v[118:119], v[24:25] op_sel:[1,0,0] op_sel_hi:[1,1,1]
	v_pk_fma_f32 v[24:25], v[8:9], v[120:121], v[24:25] op_sel:[0,0,0] op_sel_hi:[0,1,1]
	v_pk_fma_f32 v[24:25], v[8:9], v[122:123], v[24:25] op_sel:[1,0,0] op_sel_hi:[1,1,1]
	v_pk_fma_f32 v[16:17], v[124:125], v[158:159], v[10:11] op_sel:[0,1,0] op_sel_hi:[1,1,1]
	v_pk_fma_f32 v[18:19], v[126:127], v[158:159], v[8:9] op_sel:[0,1,0] op_sel_hi:[1,1,1]
	v_add_f32_dpp v15, v24, v24 row_ror:8 row_mask:0xf bank_mask:0xf bound_ctrl:1
	v_add_f32_dpp v32, v25, v25 row_ror:8 row_mask:0xf bank_mask:0xf bound_ctrl:1
	ds_read_b128 v[92:95], v48 offset:13312
	v_add_f32_dpp v15, v15, v15 row_ror:4 row_mask:0xf bank_mask:0xf bound_ctrl:1
	ds_read_b128 v[96:99], v48 offset:13568
	ds_read_b128 v[100:103], v48 offset:13824
	v_add_f32_dpp v15, v15, v15 row_ror:2 row_mask:0xf bank_mask:0xf bound_ctrl:1
	ds_read_b128 v[104:107], v48 offset:14080
	s_nop 0
	v_add_f32_dpp v30, v15, v15 row_ror:1 row_mask:0xf bank_mask:0xf bound_ctrl:1
	v_pk_fma_f32 v[10:11], v[128:129], v[30:31], v[16:17] op_sel_hi:[1,0,1] neg_lo:[0,1,0] neg_hi:[0,1,0]
	v_pk_fma_f32 v[8:9], v[130:131], v[30:31], v[18:19] op_sel_hi:[1,0,1] neg_lo:[0,1,0] neg_hi:[0,1,0]
	v_pk_mul_f32 v[24:25], v[10:11], v[132:133] op_sel:[0,0] op_sel_hi:[0,1]
	v_pk_fma_f32 v[24:25], v[10:11], v[134:135], v[24:25] op_sel:[1,0,0] op_sel_hi:[1,1,1]
	v_pk_fma_f32 v[24:25], v[8:9], v[136:137], v[24:25] op_sel:[0,0,0] op_sel_hi:[0,1,1]
	v_pk_fma_f32 v[24:25], v[8:9], v[138:139], v[24:25] op_sel:[1,0,0] op_sel_hi:[1,1,1]
	v_pk_fma_f32 v[16:17], v[76:77], v[160:161], v[10:11] op_sel_hi:[1,0,1]
	v_pk_fma_f32 v[18:19], v[78:79], v[160:161], v[8:9] op_sel_hi:[1,0,1]
	v_add_f32_dpp v15, v24, v24 row_ror:8 row_mask:0xf bank_mask:0xf bound_ctrl:1
	v_add_f32_dpp v33, v25, v25 row_ror:8 row_mask:0xf bank_mask:0xf bound_ctrl:1
	ds_read_b128 v[108:111], v48 offset:14336
	v_add_f32_dpp v15, v15, v15 row_ror:4 row_mask:0xf bank_mask:0xf bound_ctrl:1
	ds_read_b128 v[112:115], v48 offset:14592
	ds_read_b128 v[116:119], v48 offset:14848
	v_add_f32_dpp v15, v15, v15 row_ror:2 row_mask:0xf bank_mask:0xf bound_ctrl:1
	ds_read_b128 v[120:123], v48 offset:15104
	ds_read_b128 v[140:143], v48 offset:34048
	v_add_f32_dpp v30, v15, v15 row_ror:1 row_mask:0xf bank_mask:0xf bound_ctrl:1
	ds_write2st64_b32 v50, v32, v33 offset0:20 offset1:22
	s_waitcnt lgkmcnt(5)
	v_pk_fma_f32 v[10:11], v[80:81], v[30:31], v[16:17] op_sel_hi:[1,0,1] neg_lo:[0,1,0] neg_hi:[0,1,0]
	v_pk_fma_f32 v[8:9], v[82:83], v[30:31], v[18:19] op_sel_hi:[1,0,1] neg_lo:[0,1,0] neg_hi:[0,1,0]
	v_pk_mul_f32 v[24:25], v[10:11], v[84:85] op_sel:[0,0] op_sel_hi:[0,1]
	v_pk_fma_f32 v[24:25], v[10:11], v[86:87], v[24:25] op_sel:[1,0,0] op_sel_hi:[1,1,1]
	v_pk_fma_f32 v[24:25], v[8:9], v[88:89], v[24:25] op_sel:[0,0,0] op_sel_hi:[0,1,1]
	v_pk_fma_f32 v[24:25], v[8:9], v[90:91], v[24:25] op_sel:[1,0,0] op_sel_hi:[1,1,1]
	v_pk_fma_f32 v[16:17], v[92:93], v[160:161], v[10:11] op_sel:[0,1,0] op_sel_hi:[1,1,1]
	v_pk_fma_f32 v[18:19], v[94:95], v[160:161], v[8:9] op_sel:[0,1,0] op_sel_hi:[1,1,1]
	v_add_f32_dpp v15, v24, v24 row_ror:8 row_mask:0xf bank_mask:0xf bound_ctrl:1
	v_add_f32_dpp v32, v25, v25 row_ror:8 row_mask:0xf bank_mask:0xf bound_ctrl:1
	ds_read_b128 v[124:127], v48 offset:15360
	v_add_f32_dpp v15, v15, v15 row_ror:4 row_mask:0xf bank_mask:0xf bound_ctrl:1
	ds_read_b128 v[128:131], v48 offset:15616
	ds_read_b128 v[132:135], v48 offset:15872
	v_add_f32_dpp v15, v15, v15 row_ror:2 row_mask:0xf bank_mask:0xf bound_ctrl:1
	ds_read_b128 v[136:139], v48 offset:16128
	ds_read_b128 v[156:159], v49 offset:64
	v_add_f32_dpp v30, v15, v15 row_ror:1 row_mask:0xf bank_mask:0xf bound_ctrl:1
	v_pk_fma_f32 v[10:11], v[96:97], v[30:31], v[16:17] op_sel_hi:[1,0,1] neg_lo:[0,1,0] neg_hi:[0,1,0]
	v_pk_fma_f32 v[8:9], v[98:99], v[30:31], v[18:19] op_sel_hi:[1,0,1] neg_lo:[0,1,0] neg_hi:[0,1,0]
	v_pk_mul_f32 v[24:25], v[10:11], v[100:101] op_sel:[0,0] op_sel_hi:[0,1]
	v_pk_fma_f32 v[24:25], v[10:11], v[102:103], v[24:25] op_sel:[1,0,0] op_sel_hi:[1,1,1]
	v_pk_fma_f32 v[24:25], v[8:9], v[104:105], v[24:25] op_sel:[0,0,0] op_sel_hi:[0,1,1]
	v_pk_fma_f32 v[24:25], v[8:9], v[106:107], v[24:25] op_sel:[1,0,0] op_sel_hi:[1,1,1]
	v_pk_fma_f32 v[16:17], v[108:109], v[162:163], v[10:11] op_sel_hi:[1,0,1]
	v_pk_fma_f32 v[18:19], v[110:111], v[162:163], v[8:9] op_sel_hi:[1,0,1]
	v_add_f32_dpp v15, v24, v24 row_ror:8 row_mask:0xf bank_mask:0xf bound_ctrl:1
	v_add_f32_dpp v33, v25, v25 row_ror:8 row_mask:0xf bank_mask:0xf bound_ctrl:1
	ds_read_b128 v[76:79], v48 offset:16384
	v_add_f32_dpp v15, v15, v15 row_ror:4 row_mask:0xf bank_mask:0xf bound_ctrl:1
	ds_read_b128 v[80:83], v48 offset:16640
	ds_read_b128 v[84:87], v48 offset:16896
	v_add_f32_dpp v15, v15, v15 row_ror:2 row_mask:0xf bank_mask:0xf bound_ctrl:1
	ds_read_b128 v[88:91], v48 offset:17152
	ds_read_b128 v[144:147], v48 offset:33280
	v_add_f32_dpp v30, v15, v15 row_ror:1 row_mask:0xf bank_mask:0xf bound_ctrl:1
	ds_write2st64_b32 v50, v32, v33 offset0:24 offset1:26
	s_waitcnt lgkmcnt(5)
	v_pk_fma_f32 v[10:11], v[112:113], v[30:31], v[16:17] op_sel_hi:[1,0,1] neg_lo:[0,1,0] neg_hi:[0,1,0]
	v_pk_fma_f32 v[8:9], v[114:115], v[30:31], v[18:19] op_sel_hi:[1,0,1] neg_lo:[0,1,0] neg_hi:[0,1,0]
	v_pk_mul_f32 v[24:25], v[10:11], v[116:117] op_sel:[0,0] op_sel_hi:[0,1]
	v_pk_fma_f32 v[24:25], v[10:11], v[118:119], v[24:25] op_sel:[1,0,0] op_sel_hi:[1,1,1]
	v_pk_fma_f32 v[24:25], v[8:9], v[120:121], v[24:25] op_sel:[0,0,0] op_sel_hi:[0,1,1]
	v_pk_fma_f32 v[24:25], v[8:9], v[122:123], v[24:25] op_sel:[1,0,0] op_sel_hi:[1,1,1]
	v_pk_fma_f32 v[16:17], v[124:125], v[162:163], v[10:11] op_sel:[0,1,0] op_sel_hi:[1,1,1]
	v_pk_fma_f32 v[18:19], v[126:127], v[162:163], v[8:9] op_sel:[0,1,0] op_sel_hi:[1,1,1]
	v_add_f32_dpp v15, v24, v24 row_ror:8 row_mask:0xf bank_mask:0xf bound_ctrl:1
	v_add_f32_dpp v32, v25, v25 row_ror:8 row_mask:0xf bank_mask:0xf bound_ctrl:1
	ds_read_b128 v[92:95], v48 offset:17408
	v_add_f32_dpp v15, v15, v15 row_ror:4 row_mask:0xf bank_mask:0xf bound_ctrl:1
	ds_read_b128 v[96:99], v48 offset:17664
	ds_read_b128 v[100:103], v48 offset:17920
	v_add_f32_dpp v15, v15, v15 row_ror:2 row_mask:0xf bank_mask:0xf bound_ctrl:1
	ds_read_b128 v[104:107], v48 offset:18176
	s_nop 0
	v_add_f32_dpp v30, v15, v15 row_ror:1 row_mask:0xf bank_mask:0xf bound_ctrl:1
	v_pk_fma_f32 v[10:11], v[128:129], v[30:31], v[16:17] op_sel_hi:[1,0,1] neg_lo:[0,1,0] neg_hi:[0,1,0]
	v_pk_fma_f32 v[8:9], v[130:131], v[30:31], v[18:19] op_sel_hi:[1,0,1] neg_lo:[0,1,0] neg_hi:[0,1,0]
	v_pk_mul_f32 v[24:25], v[10:11], v[132:133] op_sel:[0,0] op_sel_hi:[0,1]
	v_pk_fma_f32 v[24:25], v[10:11], v[134:135], v[24:25] op_sel:[1,0,0] op_sel_hi:[1,1,1]
	v_pk_fma_f32 v[24:25], v[8:9], v[136:137], v[24:25] op_sel:[0,0,0] op_sel_hi:[0,1,1]
	v_pk_fma_f32 v[24:25], v[8:9], v[138:139], v[24:25] op_sel:[1,0,0] op_sel_hi:[1,1,1]
	s_nop 1
	v_add_f32_dpp v33, v25, v25 row_ror:8 row_mask:0xf bank_mask:0xf bound_ctrl:1
	ds_write2st64_b32 v50, v32, v33 offset0:28 offset1:30
	v_pk_mul_f32 v[10:11], v[10:11], v[140:141]
	v_pk_mul_f32 v[8:9], v[8:9], v[142:143]
	s_waitcnt lgkmcnt(6)
	v_pk_mul_f32 v[24:25], v[10:11], v[144:145]
	v_pk_fma_f32 v[24:25], v[8:9], v[146:147], v[24:25]
	v_add_f32_e32 v24, v24, v25
	v_pk_fma_f32 v[16:17], v[76:77], v[156:157], v[10:11] op_sel_hi:[1,0,1]
	v_pk_fma_f32 v[18:19], v[78:79], v[156:157], v[8:9] op_sel_hi:[1,0,1]
	v_add_f32_dpp v15, v24, v24 row_ror:8 row_mask:0xf bank_mask:0xf bound_ctrl:1
	ds_read_b128 v[108:111], v48 offset:18432
	ds_read_b128 v[112:115], v48 offset:18688
	v_add_f32_dpp v15, v15, v15 row_ror:4 row_mask:0xf bank_mask:0xf bound_ctrl:1
	ds_read_b128 v[116:119], v48 offset:18944
	ds_read_b128 v[120:123], v48 offset:19200
	v_add_f32_dpp v15, v15, v15 row_ror:2 row_mask:0xf bank_mask:0xf bound_ctrl:1
	s_nop 1
	v_add_f32_dpp v30, v15, v15 row_ror:1 row_mask:0xf bank_mask:0xf bound_ctrl:1
	s_waitcnt lgkmcnt(3)
	v_pk_fma_f32 v[10:11], v[80:81], v[30:31], v[16:17] op_sel_hi:[1,0,1] neg_lo:[0,1,0] neg_hi:[0,1,0]
	v_pk_fma_f32 v[8:9], v[82:83], v[30:31], v[18:19] op_sel_hi:[1,0,1] neg_lo:[0,1,0] neg_hi:[0,1,0]
	v_pk_mul_f32 v[24:25], v[10:11], v[84:85] op_sel:[0,0] op_sel_hi:[0,1]
	v_pk_fma_f32 v[24:25], v[10:11], v[86:87], v[24:25] op_sel:[1,0,0] op_sel_hi:[1,1,1]
	v_pk_fma_f32 v[24:25], v[8:9], v[88:89], v[24:25] op_sel:[0,0,0] op_sel_hi:[0,1,1]
	v_pk_fma_f32 v[24:25], v[8:9], v[90:91], v[24:25] op_sel:[1,0,0] op_sel_hi:[1,1,1]
	v_pk_fma_f32 v[16:17], v[92:93], v[156:157], v[10:11] op_sel:[0,1,0] op_sel_hi:[1,1,1]
	v_pk_fma_f32 v[18:19], v[94:95], v[156:157], v[8:9] op_sel:[0,1,0] op_sel_hi:[1,1,1]
	v_add_f32_dpp v15, v24, v24 row_ror:8 row_mask:0xf bank_mask:0xf bound_ctrl:1
	v_add_f32_dpp v32, v25, v25 row_ror:8 row_mask:0xf bank_mask:0xf bound_ctrl:1
	ds_read_b128 v[124:127], v48 offset:19456
	v_add_f32_dpp v15, v15, v15 row_ror:4 row_mask:0xf bank_mask:0xf bound_ctrl:1
	ds_read_b128 v[128:131], v48 offset:19712
	ds_read_b128 v[132:135], v48 offset:19968
	v_add_f32_dpp v15, v15, v15 row_ror:2 row_mask:0xf bank_mask:0xf bound_ctrl:1
	ds_read_b128 v[136:139], v48 offset:20224
	ds_read_b128 v[160:163], v49 offset:80
	v_add_f32_dpp v30, v15, v15 row_ror:1 row_mask:0xf bank_mask:0xf bound_ctrl:1
	v_pk_fma_f32 v[10:11], v[96:97], v[30:31], v[16:17] op_sel_hi:[1,0,1] neg_lo:[0,1,0] neg_hi:[0,1,0]
	v_pk_fma_f32 v[8:9], v[98:99], v[30:31], v[18:19] op_sel_hi:[1,0,1] neg_lo:[0,1,0] neg_hi:[0,1,0]
	v_pk_mul_f32 v[24:25], v[10:11], v[100:101] op_sel:[0,0] op_sel_hi:[0,1]
	v_pk_fma_f32 v[24:25], v[10:11], v[102:103], v[24:25] op_sel:[1,0,0] op_sel_hi:[1,1,1]
	v_pk_fma_f32 v[24:25], v[8:9], v[104:105], v[24:25] op_sel:[0,0,0] op_sel_hi:[0,1,1]
	v_pk_fma_f32 v[24:25], v[8:9], v[106:107], v[24:25] op_sel:[1,0,0] op_sel_hi:[1,1,1]
	v_pk_fma_f32 v[16:17], v[108:109], v[158:159], v[10:11] op_sel_hi:[1,0,1]
	v_pk_fma_f32 v[18:19], v[110:111], v[158:159], v[8:9] op_sel_hi:[1,0,1]
	v_add_f32_dpp v15, v24, v24 row_ror:8 row_mask:0xf bank_mask:0xf bound_ctrl:1
	v_add_f32_dpp v33, v25, v25 row_ror:8 row_mask:0xf bank_mask:0xf bound_ctrl:1
	ds_read_b128 v[76:79], v48 offset:20480
	v_add_f32_dpp v15, v15, v15 row_ror:4 row_mask:0xf bank_mask:0xf bound_ctrl:1
	ds_read_b128 v[80:83], v48 offset:20736
	ds_read_b128 v[84:87], v48 offset:20992
	v_add_f32_dpp v15, v15, v15 row_ror:2 row_mask:0xf bank_mask:0xf bound_ctrl:1
	ds_read_b128 v[88:91], v48 offset:21248
	s_nop 0
	v_add_f32_dpp v30, v15, v15 row_ror:1 row_mask:0xf bank_mask:0xf bound_ctrl:1
	ds_write2st64_b32 v50, v32, v33 offset0:32 offset1:34
	s_waitcnt lgkmcnt(4)
	v_pk_fma_f32 v[10:11], v[112:113], v[30:31], v[16:17] op_sel_hi:[1,0,1] neg_lo:[0,1,0] neg_hi:[0,1,0]
	v_pk_fma_f32 v[8:9], v[114:115], v[30:31], v[18:19] op_sel_hi:[1,0,1] neg_lo:[0,1,0] neg_hi:[0,1,0]
	v_pk_mul_f32 v[24:25], v[10:11], v[116:117] op_sel:[0,0] op_sel_hi:[0,1]
	v_pk_fma_f32 v[24:25], v[10:11], v[118:119], v[24:25] op_sel:[1,0,0] op_sel_hi:[1,1,1]
	v_pk_fma_f32 v[24:25], v[8:9], v[120:121], v[24:25] op_sel:[0,0,0] op_sel_hi:[0,1,1]
	v_pk_fma_f32 v[24:25], v[8:9], v[122:123], v[24:25] op_sel:[1,0,0] op_sel_hi:[1,1,1]
	v_pk_fma_f32 v[16:17], v[124:125], v[158:159], v[10:11] op_sel:[0,1,0] op_sel_hi:[1,1,1]
	v_pk_fma_f32 v[18:19], v[126:127], v[158:159], v[8:9] op_sel:[0,1,0] op_sel_hi:[1,1,1]
	v_add_f32_dpp v15, v24, v24 row_ror:8 row_mask:0xf bank_mask:0xf bound_ctrl:1
	v_add_f32_dpp v32, v25, v25 row_ror:8 row_mask:0xf bank_mask:0xf bound_ctrl:1
	ds_read_b128 v[92:95], v48 offset:21504
	v_add_f32_dpp v15, v15, v15 row_ror:4 row_mask:0xf bank_mask:0xf bound_ctrl:1
	ds_read_b128 v[96:99], v48 offset:21760
	ds_read_b128 v[100:103], v48 offset:22016
	v_add_f32_dpp v15, v15, v15 row_ror:2 row_mask:0xf bank_mask:0xf bound_ctrl:1
	ds_read_b128 v[104:107], v48 offset:22272
	s_nop 0
	v_add_f32_dpp v30, v15, v15 row_ror:1 row_mask:0xf bank_mask:0xf bound_ctrl:1
	v_pk_fma_f32 v[10:11], v[128:129], v[30:31], v[16:17] op_sel_hi:[1,0,1] neg_lo:[0,1,0] neg_hi:[0,1,0]
	v_pk_fma_f32 v[8:9], v[130:131], v[30:31], v[18:19] op_sel_hi:[1,0,1] neg_lo:[0,1,0] neg_hi:[0,1,0]
	v_pk_mul_f32 v[24:25], v[10:11], v[132:133] op_sel:[0,0] op_sel_hi:[0,1]
	v_pk_fma_f32 v[24:25], v[10:11], v[134:135], v[24:25] op_sel:[1,0,0] op_sel_hi:[1,1,1]
	v_pk_fma_f32 v[24:25], v[8:9], v[136:137], v[24:25] op_sel:[0,0,0] op_sel_hi:[0,1,1]
	v_pk_fma_f32 v[24:25], v[8:9], v[138:139], v[24:25] op_sel:[1,0,0] op_sel_hi:[1,1,1]
	v_pk_fma_f32 v[16:17], v[76:77], v[160:161], v[10:11] op_sel_hi:[1,0,1]
	v_pk_fma_f32 v[18:19], v[78:79], v[160:161], v[8:9] op_sel_hi:[1,0,1]
	v_add_f32_dpp v15, v24, v24 row_ror:8 row_mask:0xf bank_mask:0xf bound_ctrl:1
	v_add_f32_dpp v33, v25, v25 row_ror:8 row_mask:0xf bank_mask:0xf bound_ctrl:1
	ds_read_b128 v[108:111], v48 offset:22528
	v_add_f32_dpp v15, v15, v15 row_ror:4 row_mask:0xf bank_mask:0xf bound_ctrl:1
	ds_read_b128 v[112:115], v48 offset:22784
	ds_read_b128 v[116:119], v48 offset:23040
	v_add_f32_dpp v15, v15, v15 row_ror:2 row_mask:0xf bank_mask:0xf bound_ctrl:1
	ds_read_b128 v[120:123], v48 offset:23296
	ds_read_b128 v[140:143], v48 offset:34304
	v_add_f32_dpp v30, v15, v15 row_ror:1 row_mask:0xf bank_mask:0xf bound_ctrl:1
	ds_write2st64_b32 v50, v32, v33 offset0:36 offset1:38
	s_waitcnt lgkmcnt(5)
	v_pk_fma_f32 v[10:11], v[80:81], v[30:31], v[16:17] op_sel_hi:[1,0,1] neg_lo:[0,1,0] neg_hi:[0,1,0]
	v_pk_fma_f32 v[8:9], v[82:83], v[30:31], v[18:19] op_sel_hi:[1,0,1] neg_lo:[0,1,0] neg_hi:[0,1,0]
	v_pk_mul_f32 v[24:25], v[10:11], v[84:85] op_sel:[0,0] op_sel_hi:[0,1]
	v_pk_fma_f32 v[24:25], v[10:11], v[86:87], v[24:25] op_sel:[1,0,0] op_sel_hi:[1,1,1]
	v_pk_fma_f32 v[24:25], v[8:9], v[88:89], v[24:25] op_sel:[0,0,0] op_sel_hi:[0,1,1]
	v_pk_fma_f32 v[24:25], v[8:9], v[90:91], v[24:25] op_sel:[1,0,0] op_sel_hi:[1,1,1]
	v_pk_fma_f32 v[16:17], v[92:93], v[160:161], v[10:11] op_sel:[0,1,0] op_sel_hi:[1,1,1]
	v_pk_fma_f32 v[18:19], v[94:95], v[160:161], v[8:9] op_sel:[0,1,0] op_sel_hi:[1,1,1]
	v_add_f32_dpp v15, v24, v24 row_ror:8 row_mask:0xf bank_mask:0xf bound_ctrl:1
	v_add_f32_dpp v32, v25, v25 row_ror:8 row_mask:0xf bank_mask:0xf bound_ctrl:1
	ds_read_b128 v[124:127], v48 offset:23552
	v_add_f32_dpp v15, v15, v15 row_ror:4 row_mask:0xf bank_mask:0xf bound_ctrl:1
	ds_read_b128 v[128:131], v48 offset:23808
	ds_read_b128 v[132:135], v48 offset:24064
	v_add_f32_dpp v15, v15, v15 row_ror:2 row_mask:0xf bank_mask:0xf bound_ctrl:1
	ds_read_b128 v[136:139], v48 offset:24320
	ds_read_b128 v[156:159], v49 offset:96
	v_add_f32_dpp v30, v15, v15 row_ror:1 row_mask:0xf bank_mask:0xf bound_ctrl:1
	v_pk_fma_f32 v[10:11], v[96:97], v[30:31], v[16:17] op_sel_hi:[1,0,1] neg_lo:[0,1,0] neg_hi:[0,1,0]
	v_pk_fma_f32 v[8:9], v[98:99], v[30:31], v[18:19] op_sel_hi:[1,0,1] neg_lo:[0,1,0] neg_hi:[0,1,0]
	v_pk_mul_f32 v[24:25], v[10:11], v[100:101] op_sel:[0,0] op_sel_hi:[0,1]
	v_pk_fma_f32 v[24:25], v[10:11], v[102:103], v[24:25] op_sel:[1,0,0] op_sel_hi:[1,1,1]
	v_pk_fma_f32 v[24:25], v[8:9], v[104:105], v[24:25] op_sel:[0,0,0] op_sel_hi:[0,1,1]
	v_pk_fma_f32 v[24:25], v[8:9], v[106:107], v[24:25] op_sel:[1,0,0] op_sel_hi:[1,1,1]
	v_pk_fma_f32 v[16:17], v[108:109], v[162:163], v[10:11] op_sel_hi:[1,0,1]
	v_pk_fma_f32 v[18:19], v[110:111], v[162:163], v[8:9] op_sel_hi:[1,0,1]
	v_add_f32_dpp v15, v24, v24 row_ror:8 row_mask:0xf bank_mask:0xf bound_ctrl:1
	v_add_f32_dpp v33, v25, v25 row_ror:8 row_mask:0xf bank_mask:0xf bound_ctrl:1
	ds_read_b128 v[76:79], v48 offset:24576
	v_add_f32_dpp v15, v15, v15 row_ror:4 row_mask:0xf bank_mask:0xf bound_ctrl:1
	ds_read_b128 v[80:83], v48 offset:24832
	ds_read_b128 v[84:87], v48 offset:25088
	v_add_f32_dpp v15, v15, v15 row_ror:2 row_mask:0xf bank_mask:0xf bound_ctrl:1
	ds_read_b128 v[88:91], v48 offset:25344
	ds_read_b128 v[144:147], v48 offset:33536
	v_add_f32_dpp v30, v15, v15 row_ror:1 row_mask:0xf bank_mask:0xf bound_ctrl:1
	ds_write2st64_b32 v50, v32, v33 offset0:40 offset1:42
	s_waitcnt lgkmcnt(5)
	v_pk_fma_f32 v[10:11], v[112:113], v[30:31], v[16:17] op_sel_hi:[1,0,1] neg_lo:[0,1,0] neg_hi:[0,1,0]
	v_pk_fma_f32 v[8:9], v[114:115], v[30:31], v[18:19] op_sel_hi:[1,0,1] neg_lo:[0,1,0] neg_hi:[0,1,0]
	v_pk_mul_f32 v[24:25], v[10:11], v[116:117] op_sel:[0,0] op_sel_hi:[0,1]
	v_pk_fma_f32 v[24:25], v[10:11], v[118:119], v[24:25] op_sel:[1,0,0] op_sel_hi:[1,1,1]
	v_pk_fma_f32 v[24:25], v[8:9], v[120:121], v[24:25] op_sel:[0,0,0] op_sel_hi:[0,1,1]
	v_pk_fma_f32 v[24:25], v[8:9], v[122:123], v[24:25] op_sel:[1,0,0] op_sel_hi:[1,1,1]
	v_pk_fma_f32 v[16:17], v[124:125], v[162:163], v[10:11] op_sel:[0,1,0] op_sel_hi:[1,1,1]
	v_pk_fma_f32 v[18:19], v[126:127], v[162:163], v[8:9] op_sel:[0,1,0] op_sel_hi:[1,1,1]
	v_add_f32_dpp v15, v24, v24 row_ror:8 row_mask:0xf bank_mask:0xf bound_ctrl:1
	v_add_f32_dpp v32, v25, v25 row_ror:8 row_mask:0xf bank_mask:0xf bound_ctrl:1
	ds_read_b128 v[92:95], v48 offset:25600
	v_add_f32_dpp v15, v15, v15 row_ror:4 row_mask:0xf bank_mask:0xf bound_ctrl:1
	ds_read_b128 v[96:99], v48 offset:25856
	ds_read_b128 v[100:103], v48 offset:26112
	v_add_f32_dpp v15, v15, v15 row_ror:2 row_mask:0xf bank_mask:0xf bound_ctrl:1
	ds_read_b128 v[104:107], v48 offset:26368
	s_nop 0
	v_add_f32_dpp v30, v15, v15 row_ror:1 row_mask:0xf bank_mask:0xf bound_ctrl:1
	v_pk_fma_f32 v[10:11], v[128:129], v[30:31], v[16:17] op_sel_hi:[1,0,1] neg_lo:[0,1,0] neg_hi:[0,1,0]
	v_pk_fma_f32 v[8:9], v[130:131], v[30:31], v[18:19] op_sel_hi:[1,0,1] neg_lo:[0,1,0] neg_hi:[0,1,0]
	v_pk_mul_f32 v[24:25], v[10:11], v[132:133] op_sel:[0,0] op_sel_hi:[0,1]
	v_pk_fma_f32 v[24:25], v[10:11], v[134:135], v[24:25] op_sel:[1,0,0] op_sel_hi:[1,1,1]
	v_pk_fma_f32 v[24:25], v[8:9], v[136:137], v[24:25] op_sel:[0,0,0] op_sel_hi:[0,1,1]
	v_pk_fma_f32 v[24:25], v[8:9], v[138:139], v[24:25] op_sel:[1,0,0] op_sel_hi:[1,1,1]
	s_nop 1
	v_add_f32_dpp v33, v25, v25 row_ror:8 row_mask:0xf bank_mask:0xf bound_ctrl:1
	ds_write2st64_b32 v50, v32, v33 offset0:44 offset1:46
	v_pk_mul_f32 v[10:11], v[10:11], v[140:141]
	v_pk_mul_f32 v[8:9], v[8:9], v[142:143]
	s_waitcnt lgkmcnt(6)
	v_pk_mul_f32 v[24:25], v[10:11], v[144:145]
	v_pk_fma_f32 v[24:25], v[8:9], v[146:147], v[24:25]
	v_add_f32_e32 v24, v24, v25
	v_pk_fma_f32 v[16:17], v[76:77], v[156:157], v[10:11] op_sel_hi:[1,0,1]
	v_pk_fma_f32 v[18:19], v[78:79], v[156:157], v[8:9] op_sel_hi:[1,0,1]
	v_add_f32_dpp v15, v24, v24 row_ror:8 row_mask:0xf bank_mask:0xf bound_ctrl:1
	ds_read_b128 v[108:111], v48 offset:26624
	ds_read_b128 v[112:115], v48 offset:26880
	v_add_f32_dpp v15, v15, v15 row_ror:4 row_mask:0xf bank_mask:0xf bound_ctrl:1
	ds_read_b128 v[116:119], v48 offset:27136
	ds_read_b128 v[120:123], v48 offset:27392
	v_add_f32_dpp v15, v15, v15 row_ror:2 row_mask:0xf bank_mask:0xf bound_ctrl:1
	s_nop 1
	v_add_f32_dpp v30, v15, v15 row_ror:1 row_mask:0xf bank_mask:0xf bound_ctrl:1
	s_waitcnt lgkmcnt(3)
	v_pk_fma_f32 v[10:11], v[80:81], v[30:31], v[16:17] op_sel_hi:[1,0,1] neg_lo:[0,1,0] neg_hi:[0,1,0]
	v_pk_fma_f32 v[8:9], v[82:83], v[30:31], v[18:19] op_sel_hi:[1,0,1] neg_lo:[0,1,0] neg_hi:[0,1,0]
	v_pk_mul_f32 v[24:25], v[10:11], v[84:85] op_sel:[0,0] op_sel_hi:[0,1]
	v_pk_fma_f32 v[24:25], v[10:11], v[86:87], v[24:25] op_sel:[1,0,0] op_sel_hi:[1,1,1]
	v_pk_fma_f32 v[24:25], v[8:9], v[88:89], v[24:25] op_sel:[0,0,0] op_sel_hi:[0,1,1]
	v_pk_fma_f32 v[24:25], v[8:9], v[90:91], v[24:25] op_sel:[1,0,0] op_sel_hi:[1,1,1]
	v_pk_fma_f32 v[16:17], v[92:93], v[156:157], v[10:11] op_sel:[0,1,0] op_sel_hi:[1,1,1]
	v_pk_fma_f32 v[18:19], v[94:95], v[156:157], v[8:9] op_sel:[0,1,0] op_sel_hi:[1,1,1]
	v_add_f32_dpp v15, v24, v24 row_ror:8 row_mask:0xf bank_mask:0xf bound_ctrl:1
	v_add_f32_dpp v32, v25, v25 row_ror:8 row_mask:0xf bank_mask:0xf bound_ctrl:1
	ds_read_b128 v[124:127], v48 offset:27648
	v_add_f32_dpp v15, v15, v15 row_ror:4 row_mask:0xf bank_mask:0xf bound_ctrl:1
	ds_read_b128 v[128:131], v48 offset:27904
	ds_read_b128 v[132:135], v48 offset:28160
	v_add_f32_dpp v15, v15, v15 row_ror:2 row_mask:0xf bank_mask:0xf bound_ctrl:1
	ds_read_b128 v[136:139], v48 offset:28416
	ds_read_b128 v[160:163], v49 offset:112
	v_add_f32_dpp v30, v15, v15 row_ror:1 row_mask:0xf bank_mask:0xf bound_ctrl:1
	v_pk_fma_f32 v[10:11], v[96:97], v[30:31], v[16:17] op_sel_hi:[1,0,1] neg_lo:[0,1,0] neg_hi:[0,1,0]
	v_pk_fma_f32 v[8:9], v[98:99], v[30:31], v[18:19] op_sel_hi:[1,0,1] neg_lo:[0,1,0] neg_hi:[0,1,0]
	v_pk_mul_f32 v[24:25], v[10:11], v[100:101] op_sel:[0,0] op_sel_hi:[0,1]
	v_pk_fma_f32 v[24:25], v[10:11], v[102:103], v[24:25] op_sel:[1,0,0] op_sel_hi:[1,1,1]
	v_pk_fma_f32 v[24:25], v[8:9], v[104:105], v[24:25] op_sel:[0,0,0] op_sel_hi:[0,1,1]
	v_pk_fma_f32 v[24:25], v[8:9], v[106:107], v[24:25] op_sel:[1,0,0] op_sel_hi:[1,1,1]
	v_pk_fma_f32 v[16:17], v[108:109], v[158:159], v[10:11] op_sel_hi:[1,0,1]
	v_pk_fma_f32 v[18:19], v[110:111], v[158:159], v[8:9] op_sel_hi:[1,0,1]
	v_add_f32_dpp v15, v24, v24 row_ror:8 row_mask:0xf bank_mask:0xf bound_ctrl:1
	v_add_f32_dpp v33, v25, v25 row_ror:8 row_mask:0xf bank_mask:0xf bound_ctrl:1
	ds_read_b128 v[76:79], v48 offset:28672
	v_add_f32_dpp v15, v15, v15 row_ror:4 row_mask:0xf bank_mask:0xf bound_ctrl:1
	ds_read_b128 v[80:83], v48 offset:28928
	ds_read_b128 v[84:87], v48 offset:29184
	v_add_f32_dpp v15, v15, v15 row_ror:2 row_mask:0xf bank_mask:0xf bound_ctrl:1
	ds_read_b128 v[88:91], v48 offset:29440
	s_nop 0
	v_add_f32_dpp v30, v15, v15 row_ror:1 row_mask:0xf bank_mask:0xf bound_ctrl:1
	ds_write2st64_b32 v50, v32, v33 offset0:48 offset1:50
	ds_read_b128 v[56:59], v52
	s_waitcnt lgkmcnt(5)
	v_pk_fma_f32 v[10:11], v[112:113], v[30:31], v[16:17] op_sel_hi:[1,0,1] neg_lo:[0,1,0] neg_hi:[0,1,0]
	v_pk_fma_f32 v[8:9], v[114:115], v[30:31], v[18:19] op_sel_hi:[1,0,1] neg_lo:[0,1,0] neg_hi:[0,1,0]
	v_pk_mul_f32 v[24:25], v[10:11], v[116:117] op_sel:[0,0] op_sel_hi:[0,1]
	v_pk_fma_f32 v[24:25], v[10:11], v[118:119], v[24:25] op_sel:[1,0,0] op_sel_hi:[1,1,1]
	v_pk_fma_f32 v[24:25], v[8:9], v[120:121], v[24:25] op_sel:[0,0,0] op_sel_hi:[0,1,1]
	v_pk_fma_f32 v[24:25], v[8:9], v[122:123], v[24:25] op_sel:[1,0,0] op_sel_hi:[1,1,1]
	v_pk_fma_f32 v[16:17], v[124:125], v[158:159], v[10:11] op_sel:[0,1,0] op_sel_hi:[1,1,1]
	v_pk_fma_f32 v[18:19], v[126:127], v[158:159], v[8:9] op_sel:[0,1,0] op_sel_hi:[1,1,1]
	v_add_f32_dpp v15, v24, v24 row_ror:8 row_mask:0xf bank_mask:0xf bound_ctrl:1
	v_add_f32_dpp v32, v25, v25 row_ror:8 row_mask:0xf bank_mask:0xf bound_ctrl:1
	ds_read_b128 v[92:95], v48 offset:29696
	v_add_f32_dpp v15, v15, v15 row_ror:4 row_mask:0xf bank_mask:0xf bound_ctrl:1
	ds_read_b128 v[96:99], v48 offset:29952
	ds_read_b128 v[100:103], v48 offset:30208
	v_add_f32_dpp v15, v15, v15 row_ror:2 row_mask:0xf bank_mask:0xf bound_ctrl:1
	ds_read_b128 v[104:107], v48 offset:30464
	s_nop 0
	v_add_f32_dpp v30, v15, v15 row_ror:1 row_mask:0xf bank_mask:0xf bound_ctrl:1
	s_waitcnt lgkmcnt(4)
	v_min_u32_e32 v56, v56, v57
	v_min3_u32 v56, v56, v58, v59
	v_pk_fma_f32 v[10:11], v[128:129], v[30:31], v[16:17] op_sel_hi:[1,0,1] neg_lo:[0,1,0] neg_hi:[0,1,0]
	v_pk_fma_f32 v[8:9], v[130:131], v[30:31], v[18:19] op_sel_hi:[1,0,1] neg_lo:[0,1,0] neg_hi:[0,1,0]
	v_pk_mul_f32 v[24:25], v[10:11], v[132:133] op_sel:[0,0] op_sel_hi:[0,1]
	v_pk_fma_f32 v[24:25], v[10:11], v[134:135], v[24:25] op_sel:[1,0,0] op_sel_hi:[1,1,1]
	v_pk_fma_f32 v[24:25], v[8:9], v[136:137], v[24:25] op_sel:[0,0,0] op_sel_hi:[0,1,1]
	v_pk_fma_f32 v[24:25], v[8:9], v[138:139], v[24:25] op_sel:[1,0,0] op_sel_hi:[1,1,1]
	v_pk_fma_f32 v[16:17], v[76:77], v[160:161], v[10:11] op_sel_hi:[1,0,1]
	v_pk_fma_f32 v[18:19], v[78:79], v[160:161], v[8:9] op_sel_hi:[1,0,1]
	v_add_f32_dpp v15, v24, v24 row_ror:8 row_mask:0xf bank_mask:0xf bound_ctrl:1
	v_add_f32_dpp v33, v25, v25 row_ror:8 row_mask:0xf bank_mask:0xf bound_ctrl:1
	ds_read_b128 v[108:111], v48 offset:30720
	v_add_f32_dpp v15, v15, v15 row_ror:4 row_mask:0xf bank_mask:0xf bound_ctrl:1
	ds_read_b128 v[112:115], v48 offset:30976
	ds_read_b128 v[116:119], v48 offset:31232
	v_add_f32_dpp v15, v15, v15 row_ror:2 row_mask:0xf bank_mask:0xf bound_ctrl:1
	ds_read_b128 v[120:123], v48 offset:31488
	ds_read_b128 v[140:143], v48 offset:34560
	v_add_f32_dpp v30, v15, v15 row_ror:1 row_mask:0xf bank_mask:0xf bound_ctrl:1
	ds_write2st64_b32 v50, v32, v33 offset0:52 offset1:54
	s_waitcnt lgkmcnt(5)
	v_pk_fma_f32 v[10:11], v[80:81], v[30:31], v[16:17] op_sel_hi:[1,0,1] neg_lo:[0,1,0] neg_hi:[0,1,0]
	v_pk_fma_f32 v[8:9], v[82:83], v[30:31], v[18:19] op_sel_hi:[1,0,1] neg_lo:[0,1,0] neg_hi:[0,1,0]
	v_pk_mul_f32 v[24:25], v[10:11], v[84:85] op_sel:[0,0] op_sel_hi:[0,1]
	v_pk_fma_f32 v[24:25], v[10:11], v[86:87], v[24:25] op_sel:[1,0,0] op_sel_hi:[1,1,1]
	v_pk_fma_f32 v[24:25], v[8:9], v[88:89], v[24:25] op_sel:[0,0,0] op_sel_hi:[0,1,1]
	v_pk_fma_f32 v[24:25], v[8:9], v[90:91], v[24:25] op_sel:[1,0,0] op_sel_hi:[1,1,1]
	v_pk_fma_f32 v[16:17], v[92:93], v[160:161], v[10:11] op_sel:[0,1,0] op_sel_hi:[1,1,1]
	v_pk_fma_f32 v[18:19], v[94:95], v[160:161], v[8:9] op_sel:[0,1,0] op_sel_hi:[1,1,1]
	v_add_f32_dpp v15, v24, v24 row_ror:8 row_mask:0xf bank_mask:0xf bound_ctrl:1
	v_add_f32_dpp v32, v25, v25 row_ror:8 row_mask:0xf bank_mask:0xf bound_ctrl:1
	ds_read_b128 v[124:127], v48 offset:31744
	v_add_f32_dpp v15, v15, v15 row_ror:4 row_mask:0xf bank_mask:0xf bound_ctrl:1
	ds_read_b128 v[128:131], v48 offset:32000
	ds_read_b128 v[132:135], v48 offset:32256
	v_add_f32_dpp v15, v15, v15 row_ror:2 row_mask:0xf bank_mask:0xf bound_ctrl:1
	ds_read_b128 v[136:139], v48 offset:32512
	s_nop 0
	v_add_f32_dpp v30, v15, v15 row_ror:1 row_mask:0xf bank_mask:0xf bound_ctrl:1
	v_readfirstlane_b32 s54, v56
	s_add_u32 s64, s6, 2
	s_cmp_lt_u32 s54, s64
	s_cbranch_scc1 .Lss_spin_1
.Lss_ok_1:
	v_pk_fma_f32 v[10:11], v[96:97], v[30:31], v[16:17] op_sel_hi:[1,0,1] neg_lo:[0,1,0] neg_hi:[0,1,0]
	v_pk_fma_f32 v[8:9], v[98:99], v[30:31], v[18:19] op_sel_hi:[1,0,1] neg_lo:[0,1,0] neg_hi:[0,1,0]
	v_pk_mul_f32 v[24:25], v[10:11], v[100:101] op_sel:[0,0] op_sel_hi:[0,1]
	v_pk_fma_f32 v[24:25], v[10:11], v[102:103], v[24:25] op_sel:[1,0,0] op_sel_hi:[1,1,1]
	v_pk_fma_f32 v[24:25], v[8:9], v[104:105], v[24:25] op_sel:[0,0,0] op_sel_hi:[0,1,1]
	v_pk_fma_f32 v[24:25], v[8:9], v[106:107], v[24:25] op_sel:[1,0,0] op_sel_hi:[1,1,1]
	v_pk_fma_f32 v[16:17], v[108:109], v[162:163], v[10:11] op_sel_hi:[1,0,1]
	v_pk_fma_f32 v[18:19], v[110:111], v[162:163], v[8:9] op_sel_hi:[1,0,1]
	v_add_f32_dpp v15, v24, v24 row_ror:8 row_mask:0xf bank_mask:0xf bound_ctrl:1
	v_add_f32_dpp v33, v25, v25 row_ror:8 row_mask:0xf bank_mask:0xf bound_ctrl:1
	ds_read_b128 v[76:79], v34 offset:0
	v_add_f32_dpp v15, v15, v15 row_ror:4 row_mask:0xf bank_mask:0xf bound_ctrl:1
	ds_read_b128 v[80:83], v34 offset:256
	ds_read_b128 v[84:87], v34 offset:512
	v_add_f32_dpp v15, v15, v15 row_ror:2 row_mask:0xf bank_mask:0xf bound_ctrl:1
	ds_read_b128 v[88:91], v34 offset:768
	ds_read_b128 v[144:147], v34 offset:32768
	v_add_f32_dpp v30, v15, v15 row_ror:1 row_mask:0xf bank_mask:0xf bound_ctrl:1
	ds_write2st64_b32 v50, v32, v33 offset0:56 offset1:58
	ds_read_b128 v[156:159], v35 offset:0
	s_waitcnt lgkmcnt(6)
	v_pk_fma_f32 v[10:11], v[112:113], v[30:31], v[16:17] op_sel_hi:[1,0,1] neg_lo:[0,1,0] neg_hi:[0,1,0]
	v_pk_fma_f32 v[8:9], v[114:115], v[30:31], v[18:19] op_sel_hi:[1,0,1] neg_lo:[0,1,0] neg_hi:[0,1,0]
	v_pk_mul_f32 v[24:25], v[10:11], v[116:117] op_sel:[0,0] op_sel_hi:[0,1]
	v_pk_fma_f32 v[24:25], v[10:11], v[118:119], v[24:25] op_sel:[1,0,0] op_sel_hi:[1,1,1]
	v_pk_fma_f32 v[24:25], v[8:9], v[120:121], v[24:25] op_sel:[0,0,0] op_sel_hi:[0,1,1]
	v_pk_fma_f32 v[24:25], v[8:9], v[122:123], v[24:25] op_sel:[1,0,0] op_sel_hi:[1,1,1]
	v_pk_fma_f32 v[16:17], v[124:125], v[162:163], v[10:11] op_sel:[0,1,0] op_sel_hi:[1,1,1]
	v_pk_fma_f32 v[18:19], v[126:127], v[162:163], v[8:9] op_sel:[0,1,0] op_sel_hi:[1,1,1]
	v_add_f32_dpp v15, v24, v24 row_ror:8 row_mask:0xf bank_mask:0xf bound_ctrl:1
	v_add_f32_dpp v32, v25, v25 row_ror:8 row_mask:0xf bank_mask:0xf bound_ctrl:1
	ds_read_b128 v[92:95], v34 offset:1024
	v_add_f32_dpp v15, v15, v15 row_ror:4 row_mask:0xf bank_mask:0xf bound_ctrl:1
	ds_read_b128 v[96:99], v34 offset:1280
	ds_read_b128 v[100:103], v34 offset:1536
	v_add_f32_dpp v15, v15, v15 row_ror:2 row_mask:0xf bank_mask:0xf bound_ctrl:1
	ds_read_b128 v[104:107], v34 offset:1792
	s_nop 0
	v_add_f32_dpp v30, v15, v15 row_ror:1 row_mask:0xf bank_mask:0xf bound_ctrl:1
	v_pk_fma_f32 v[10:11], v[128:129], v[30:31], v[16:17] op_sel_hi:[1,0,1] neg_lo:[0,1,0] neg_hi:[0,1,0]
	v_pk_fma_f32 v[8:9], v[130:131], v[30:31], v[18:19] op_sel_hi:[1,0,1] neg_lo:[0,1,0] neg_hi:[0,1,0]
	v_pk_mul_f32 v[24:25], v[10:11], v[132:133] op_sel:[0,0] op_sel_hi:[0,1]
	v_pk_fma_f32 v[24:25], v[10:11], v[134:135], v[24:25] op_sel:[1,0,0] op_sel_hi:[1,1,1]
	v_pk_fma_f32 v[24:25], v[8:9], v[136:137], v[24:25] op_sel:[0,0,0] op_sel_hi:[0,1,1]
	v_pk_fma_f32 v[24:25], v[8:9], v[138:139], v[24:25] op_sel:[1,0,0] op_sel_hi:[1,1,1]
	s_nop 1
	v_add_f32_dpp v33, v25, v25 row_ror:8 row_mask:0xf bank_mask:0xf bound_ctrl:1
	ds_write2st64_b32 v50, v32, v33 offset0:60 offset1:62
	v_pk_mul_f32 v[10:11], v[10:11], v[140:141]
	v_pk_mul_f32 v[8:9], v[8:9], v[142:143]
	s_waitcnt lgkmcnt(7)
	v_pk_mul_f32 v[24:25], v[10:11], v[144:145]
	v_pk_fma_f32 v[24:25], v[8:9], v[146:147], v[24:25]
	v_add_f32_e32 v24, v24, v25
	s_waitcnt lgkmcnt(5)
	v_pk_fma_f32 v[16:17], v[76:77], v[156:157], v[10:11] op_sel_hi:[1,0,1]
	v_pk_fma_f32 v[18:19], v[78:79], v[156:157], v[8:9] op_sel_hi:[1,0,1]
	v_add_f32_dpp v15, v24, v24 row_ror:8 row_mask:0xf bank_mask:0xf bound_ctrl:1
	v_add_u32_e32 v51, 1, v51
	s_add_u32 s6, s6, 1
	v_add_f32_dpp v15, v15, v15 row_ror:4 row_mask:0xf bank_mask:0xf bound_ctrl:1
	ds_write_b32 v53, v51
	ds_read_b128 v[108:111], v34 offset:2048
	v_add_f32_dpp v15, v15, v15 row_ror:2 row_mask:0xf bank_mask:0xf bound_ctrl:1
	ds_read_b128 v[112:115], v34 offset:2304
	ds_read_b128 v[116:119], v34 offset:2560
	v_add_f32_dpp v30, v15, v15 row_ror:1 row_mask:0xf bank_mask:0xf bound_ctrl:1
	ds_read_b128 v[120:123], v34 offset:2816
	s_cmp_lt_u32 s6, 0x100
	s_cbranch_scc1 .Lsc_S_loop
	s_waitcnt lgkmcnt(0)
	s_branch .Lsc_item_end
	s_nop 0
	s_nop 0
	s_nop 0
	s_nop 0
	s_nop 0
	s_nop 0
	s_nop 0
	s_nop 0
	s_nop 0
	s_nop 0
	s_nop 0
	s_nop 0
	s_nop 0
	s_nop 0
	s_nop 0
	s_nop 0
	s_nop 0
